# GEMM: first K iteration peeled with C=0 instead of clearing 128 accumulators per unit
# speedup vs baseline: 1.0047x; 1.0028x over previous
; #define PG8_STAGE(bufoff, gbase, voff) do { _Pragma("unroll") for (int _i = 0; _i < 2; ++_i) \
;         __builtin_amdgcn_global_load_lds((const unsigned*)((const char*)(gbase) + (voff)[_i]), (PG8_LAS unsigned*)(lds + (bufoff) + ldsw + _i * 8192), 16, 0, 0); } while (0)
; #define PG8_LDA(dst, b, h) do { _Pragma("unroll") for (int m = 0; m < 4; ++m) _Pragma("unroll") for (int k = 0; k < 2; ++k) dst[m][k] = *(const PG8_LAS bf16x8*)(lds + PG8_SA(b, h) + aoffk[k] + m * 2048); } while (0)
; #define PG8_WAIT_V(n) asm volatile("s_waitcnt vmcnt(" #n ")" ::: "memory")
; #define PG8_BAR __builtin_amdgcn_s_barrier()
; template <class Epi, class Sched, bool ALIGN_EPI = false, bool SP2 = false>
; __device__ __forceinline__ void gemm_phase(PG8_LAS unsigned char* lds, const Gemm g, const Sched& S, const Epi& E) {
;     ...
;     f32x4 acc[2][2][4][2];
; #pragma unroll
;     for (int a = 0; a < 2; ++a)
; #pragma unroll
;         for (int b = 0; b < 2; ++b)
; #pragma unroll
;             for (int m = 0; m < 4; ++m)
; #pragma unroll
;                 for (int n = 0; n < 2; ++n) acc[a][b][m][n] = (f32x4){0.f, 0.f, 0.f, 0.f};
;     ...
;         const bool has_next = S.next(ui + 1, nxt);
;         const char* nA = has_next ? (const char*)g.A + (size_t)nxt.pm * tstepA + (size_t)nxt.kt0 * kstep : cA; const char* nB = has_next ? (const char*)g.Bt + (size_t)nxt.pn * tstepB + (size_t)nxt.kt0 * kstep : cB;
;         const int nt = cur.nt;
;         for (int t = 0; t < nt; t += 2) {
;             const bool last = (t == nt - 2);
;             const char* a1 = cA + (size_t)(t + 1) * kstep;
;             const char* a2 = last ? nA : cA + (size_t)(t + 2) * kstep; const char* b2 = last ? nB : cB + (size_t)(t + 2) * kstep;
;             const char* a3 = a2 + kstep; const char* b3 = b2 + kstep;
;             if (last && has_next) S.a_ready(nxt);
;             if constexpr (SP2) {
;             PG8_LDB(B0, 0, 0); PG8_LDB(B1, 0, 1); PG8_SCHED; PG8_LDA(At, 0, 0); PG8_STAGE(PG8_SA(1, 1), a1 + hstepA, voffA);
;             PG8_WAIT_V(8); PG8_WAIT_L(0); PG8_BAR; PG8_MMA(0, 0, At, B0); PG8_MMA(0, 1, At, B1); PG8_BAR; PG8_SCHED;
;             PG8_LDA(At, 0, 1); PG8_STAGE(PG8_SB(0, 0), b2, voffB); PG8_STAGE(PG8_SB(0, 1), b2 + hstepB, voffB); PG8_STAGE(PG8_SA(0, 0), a2, voffA);
;             PG8_WAIT_V(8); PG8_WAIT_L(0); PG8_BAR; PG8_MMA(1, 0, At, B0); PG8_MMA(1, 1, At, B1); PG8_BAR; PG8_SCHED;
.LBB0_295:
	s_ashr_i32 s11, s10, 31
	s_lshl_b64 s[14:15], s[10:11], 20
	s_add_u32 s14, s28, s14
	s_addc_u32 s15, s29, s15
	s_and_b64 s[16:17], s[12:13], exec
	s_cselect_b32 s11, s15, s21
	s_cselect_b32 s33, s14, s20
	s_ashr_i32 s9, s8, 31
	s_lshl_b64 s[16:17], s[8:9], 20
	s_add_u32 s16, s30, s16
	s_addc_u32 s17, s31, s17
	s_and_b64 s[24:25], s[12:13], exec
	s_cselect_b32 s9, s17, s23
	s_cselect_b32 s43, s16, s22
	s_add_u32 s20, s20, 0x80080
	s_addc_u32 s21, s21, 0
	s_add_u32 s44, s22, 0x100
	s_addc_u32 s45, s23, 0
	s_mov_b32 s46, -2
	v_readlane_b32 s52, v253, 30
	v_readlane_b32 s53, v253, 31
	s_mov_b64 s[56:57], 0x80
.Lgemm_first_0:
	s_add_u32 s22, s20, 0xfff80080
	s_addc_u32 s23, s21, -1
	s_add_i32 s47, 0, 0x10000
	s_cmp_eq_u32 s46, 28
	s_cselect_b32 s25, s11, s23
	s_cselect_b32 s24, s33, s22
	s_cselect_b32 s23, s9, s45
	s_cselect_b32 s22, s43, s44
	s_add_i32 s50, 0, 0x14000
	v_add_u32_e32 v142, s47, v147
	v_add_u32_e32 v156, s47, v148
	v_add_u32_e32 v168, s50, v147
	v_add_u32_e32 v176, s50, v148
	ds_read_b128 v[142:145], v142
	ds_read_b128 v[156:159], v156
	ds_read_b128 v[160:163], v150
	ds_read_b128 v[164:167], v151
	ds_read_b128 v[172:175], v168
	ds_read_b128 v[176:179], v176
	ds_read_b128 v[180:183], v152
	ds_read_b128 v[184:187], v153
	v_lshl_add_u64 v[212:213], s[20:21], 0, v[138:139]
	s_add_i32 m0, s36, 0xc000
	ds_read_b128 v[188:191], v154
	ds_read_b128 v[192:195], v154 offset:1024
	ds_read_b128 v[196:199], v154 offset:2048
	ds_read_b128 v[200:203], v154 offset:3072
	ds_read_b128 v[204:207], v154 offset:4096
	ds_read_b128 v[208:211], v154 offset:5120
	ds_read_b128 v[226:229], v154 offset:6144
	ds_read_b128 v[230:233], v154 offset:7168
	global_load_lds_dwordx4 v[212:213], off
	v_lshl_add_u64 v[212:213], s[20:21], 0, v[140:141]
	s_add_i32 m0, s36, 0xe000
	s_nop 0
	global_load_lds_dwordx4 v[212:213], off
	s_waitcnt vmcnt(8)
	s_waitcnt lgkmcnt(0)
	s_barrier
	v_mfma_f32_16x16x32_bf16 v[128:131], v[142:145], v[188:191], 0
	v_mfma_f32_16x16x32_bf16 v[120:123], v[160:163], v[188:191], 0
	v_mfma_f32_16x16x32_bf16 v[112:115], v[142:145], v[196:199], 0
	v_mfma_f32_16x16x32_bf16 v[104:107], v[160:163], v[196:199], 0
	v_mfma_f32_16x16x32_bf16 v[96:99], v[142:145], v[204:207], 0
	v_mfma_f32_16x16x32_bf16 v[88:91], v[160:163], v[204:207], 0
	v_mfma_f32_16x16x32_bf16 v[80:83], v[142:145], v[226:229], 0
	v_mfma_f32_16x16x32_bf16 v[72:75], v[160:163], v[226:229], 0
	v_mfma_f32_16x16x32_bf16 v[128:131], v[156:159], v[192:195], v[128:131]
	v_mfma_f32_16x16x32_bf16 v[120:123], v[164:167], v[192:195], v[120:123]
	v_mfma_f32_16x16x32_bf16 v[112:115], v[156:159], v[200:203], v[112:115]
	v_mfma_f32_16x16x32_bf16 v[104:107], v[164:167], v[200:203], v[104:107]
	v_mfma_f32_16x16x32_bf16 v[96:99], v[156:159], v[208:211], v[96:99]
	v_mfma_f32_16x16x32_bf16 v[88:91], v[164:167], v[208:211], v[88:91]
	v_mfma_f32_16x16x32_bf16 v[80:83], v[156:159], v[230:233], v[80:83]
	v_mfma_f32_16x16x32_bf16 v[72:75], v[164:167], v[230:233], v[72:75]
	v_mfma_f32_16x16x32_bf16 v[124:127], v[172:175], v[188:191], 0
	v_mfma_f32_16x16x32_bf16 v[116:119], v[180:183], v[188:191], 0
	v_mfma_f32_16x16x32_bf16 v[108:111], v[172:175], v[196:199], 0
	v_mfma_f32_16x16x32_bf16 v[100:103], v[180:183], v[196:199], 0
	v_mfma_f32_16x16x32_bf16 v[92:95], v[172:175], v[204:207], 0
	v_mfma_f32_16x16x32_bf16 v[84:87], v[180:183], v[204:207], 0
	v_mfma_f32_16x16x32_bf16 v[76:79], v[172:175], v[226:229], 0
	v_mfma_f32_16x16x32_bf16 v[68:71], v[180:183], v[226:229], 0
	v_mfma_f32_16x16x32_bf16 v[124:127], v[176:179], v[192:195], v[124:127]
	v_mfma_f32_16x16x32_bf16 v[116:119], v[184:187], v[192:195], v[116:119]
	v_mfma_f32_16x16x32_bf16 v[108:111], v[176:179], v[200:203], v[108:111]
	v_mfma_f32_16x16x32_bf16 v[100:103], v[184:187], v[200:203], v[100:103]
	v_mfma_f32_16x16x32_bf16 v[92:95], v[176:179], v[208:211], v[92:95]
	v_mfma_f32_16x16x32_bf16 v[84:87], v[184:187], v[208:211], v[84:87]
	v_mfma_f32_16x16x32_bf16 v[76:79], v[176:179], v[230:233], v[76:79]
	v_mfma_f32_16x16x32_bf16 v[68:71], v[184:187], v[230:233], v[68:71]
	s_barrier
	s_add_i32 s47, s47, s34
	v_lshl_add_u64 v[212:213], s[22:23], 0, v[2:3]
	s_mov_b32 m0, s47
	ds_read_b128 v[188:191], v154 offset:16384
	ds_read_b128 v[192:195], v154 offset:17408
	ds_read_b128 v[196:199], v154 offset:18432
	ds_read_b128 v[200:203], v154 offset:19456
	ds_read_b128 v[204:207], v154 offset:20480
	ds_read_b128 v[208:211], v154 offset:21504
	ds_read_b128 v[226:229], v154 offset:22528
	ds_read_b128 v[230:233], v154 offset:23552
	global_load_lds_dwordx4 v[212:213], off
	s_add_i32 m0, s47, 0x2000
	s_add_u32 s48, s22, 0x80000
	v_lshl_add_u64 v[234:235], s[22:23], 0, v[132:133]
	s_addc_u32 s49, s23, 0
	s_add_i32 s47, s50, s34
	global_load_lds_dwordx4 v[234:235], off
	v_lshl_add_u64 v[236:237], s[48:49], 0, v[2:3]
	s_mov_b32 m0, s47
	v_lshl_add_u64 v[238:239], s[24:25], 0, v[134:135]
	global_load_lds_dwordx4 v[236:237], off
	v_lshl_add_u64 v[236:237], s[48:49], 0, v[132:133]
	s_add_i32 m0, s47, 0x2000
	s_nop 0
	global_load_lds_dwordx4 v[236:237], off
	v_lshl_add_u64 v[236:237], s[24:25], 0, v[136:137]
	s_mov_b32 m0, s36
	s_nop 0
	global_load_lds_dwordx4 v[236:237], off
	s_mov_b32 m0, s37
	s_nop 0
	global_load_lds_dwordx4 v[238:239], off
	s_waitcnt vmcnt(8)
	s_waitcnt lgkmcnt(0)
	s_barrier
; #define PG8_STAGE(bufoff, gbase, voff) do { _Pragma("unroll") for (int _i = 0; _i < 2; ++_i) \
;         __builtin_amdgcn_global_load_lds((const unsigned*)((const char*)(gbase) + (voff)[_i]), (PG8_LAS unsigned*)(lds + (bufoff) + ldsw + _i * 8192), 16, 0, 0); } while (0)
; #define PG8_LDA(dst, b, h) do { _Pragma("unroll") for (int m = 0; m < 4; ++m) _Pragma("unroll") for (int k = 0; k < 2; ++k) dst[m][k] = *(const PG8_LAS bf16x8*)(lds + PG8_SA(b, h) + aoffk[k] + m * 2048); } while (0)
; #define PG8_LDB(dst, b, h) do { _Pragma("unroll") for (int n = 0; n < 2; ++n) _Pragma("unroll") for (int k = 0; k < 2; ++k) dst[n][k] = *(const PG8_LAS bf16x8*)(lds + PG8_SB(b, h) + boffk[k] + n * 2048); } while (0)
; #define PG8_MMA(ai, bj, At, Bt) do { __builtin_amdgcn_s_setprio(1); _Pragma("unroll") for (int m = 0; m < 4; ++m) _Pragma("unroll") for (int n = 0; n < 2; ++n) _Pragma("unroll") for (int k = 0; k < 2; ++k) \
;         acc[ai][bj][m][n] = __builtin_amdgcn_mfma_f32_16x16x32_bf16(Bt[n][k], At[m][k], acc[ai][bj][m][n], 0, 0, 0); __builtin_amdgcn_s_setprio(0); } while (0)
; #define PG8_WAIT_V(n) asm volatile("s_waitcnt vmcnt(" #n ")" ::: "memory")
; #define PG8_WAIT_L(n) asm volatile("s_waitcnt lgkmcnt(" #n ")" ::: "memory")
; #define PG8_BAR __builtin_amdgcn_s_barrier()
; #define PG8_SCHED __builtin_amdgcn_sched_barrier(0)
; template <class Epi, class Sched, bool ALIGN_EPI = false, bool SP2 = false>
; __device__ __forceinline__ void gemm_phase(PG8_LAS unsigned char* lds, const Gemm g, const Sched& S, const Epi& E) {
;     ...
;             PG8_LDA(At, 0, 1); PG8_STAGE(PG8_SB(0, 0), b2, voffB); PG8_STAGE(PG8_SB(0, 1), b2 + hstepB, voffB); PG8_STAGE(PG8_SA(0, 0), a2, voffA);
;             PG8_WAIT_V(8); PG8_WAIT_L(0); PG8_BAR; PG8_MMA(1, 0, At, B0); PG8_MMA(1, 1, At, B1); PG8_BAR; PG8_SCHED;
;             PG8_LDB(B0, 1, 0); PG8_LDB(B1, 1, 1); PG8_SCHED; PG8_LDA(At, 1, 0); PG8_STAGE(PG8_SA(0, 1), a2 + hstepA, voffA);
;             PG8_WAIT_V(8); PG8_WAIT_L(0); PG8_BAR; PG8_MMA(0, 0, At, B0); PG8_MMA(0, 1, At, B1); PG8_BAR; PG8_SCHED;
	v_mfma_f32_16x16x32_bf16 v[64:67], v[142:145], v[188:191], 0
	v_mfma_f32_16x16x32_bf16 v[56:59], v[160:163], v[188:191], 0
	v_mfma_f32_16x16x32_bf16 v[48:51], v[142:145], v[196:199], 0
	v_mfma_f32_16x16x32_bf16 v[40:43], v[160:163], v[196:199], 0
	v_mfma_f32_16x16x32_bf16 v[32:35], v[142:145], v[204:207], 0
	v_mfma_f32_16x16x32_bf16 v[24:27], v[160:163], v[204:207], 0
	v_mfma_f32_16x16x32_bf16 v[16:19], v[142:145], v[226:229], 0
	v_mfma_f32_16x16x32_bf16 v[8:11], v[160:163], v[226:229], 0
	v_mfma_f32_16x16x32_bf16 v[64:67], v[156:159], v[192:195], v[64:67]
	v_mfma_f32_16x16x32_bf16 v[56:59], v[164:167], v[192:195], v[56:59]
	v_mfma_f32_16x16x32_bf16 v[48:51], v[156:159], v[200:203], v[48:51]
	v_mfma_f32_16x16x32_bf16 v[40:43], v[164:167], v[200:203], v[40:43]
	v_mfma_f32_16x16x32_bf16 v[32:35], v[156:159], v[208:211], v[32:35]
	v_mfma_f32_16x16x32_bf16 v[24:27], v[164:167], v[208:211], v[24:27]
	v_mfma_f32_16x16x32_bf16 v[16:19], v[156:159], v[230:233], v[16:19]
	v_mfma_f32_16x16x32_bf16 v[8:11], v[164:167], v[230:233], v[8:11]
	v_mfma_f32_16x16x32_bf16 v[60:63], v[172:175], v[188:191], 0
	v_mfma_f32_16x16x32_bf16 v[52:55], v[180:183], v[188:191], 0
	v_mfma_f32_16x16x32_bf16 v[44:47], v[172:175], v[196:199], 0
	v_mfma_f32_16x16x32_bf16 v[36:39], v[180:183], v[196:199], 0
	v_mfma_f32_16x16x32_bf16 v[28:31], v[172:175], v[204:207], 0
	v_mfma_f32_16x16x32_bf16 v[20:23], v[180:183], v[204:207], 0
	v_mfma_f32_16x16x32_bf16 v[12:15], v[172:175], v[226:229], 0
	v_mfma_f32_16x16x32_bf16 v[4:7], v[180:183], v[226:229], 0
	v_mfma_f32_16x16x32_bf16 v[60:63], v[176:179], v[192:195], v[60:63]
	v_mfma_f32_16x16x32_bf16 v[52:55], v[184:187], v[192:195], v[52:55]
	v_mfma_f32_16x16x32_bf16 v[44:47], v[176:179], v[200:203], v[44:47]
	v_mfma_f32_16x16x32_bf16 v[36:39], v[184:187], v[200:203], v[36:39]
	v_mfma_f32_16x16x32_bf16 v[28:31], v[176:179], v[208:211], v[28:31]
	v_mfma_f32_16x16x32_bf16 v[20:23], v[184:187], v[208:211], v[20:23]
	v_mfma_f32_16x16x32_bf16 v[12:15], v[176:179], v[230:233], v[12:15]
	v_mfma_f32_16x16x32_bf16 v[4:7], v[184:187], v[230:233], v[4:7]
	s_barrier
	s_add_i32 s47, 0, 0x18000
	s_add_i32 s48, 0, 0x1c000
	v_add_u32_e32 v142, s47, v147
	v_add_u32_e32 v156, s47, v148
	v_add_u32_e32 v164, s52, v148
	v_add_u32_e32 v168, s48, v147
	v_add_u32_e32 v176, s48, v148
	ds_read_b128 v[142:145], v142
	ds_read_b128 v[156:159], v156
	ds_read_b128 v[160:163], v155
	ds_read_b128 v[164:167], v164
	ds_read_b128 v[172:175], v168
	ds_read_b128 v[176:179], v176
	v_add_u32_e32 v168, s53, v147
	v_add_u32_e32 v184, s53, v148
	ds_read_b128 v[180:183], v168
	ds_read_b128 v[184:187], v184
	s_add_u32 s24, s24, 0x80000
	s_addc_u32 s25, s25, 0
	s_mov_b32 m0, s38
	v_lshl_add_u64 v[240:241], s[24:25], 0, v[136:137]
	ds_read_b128 v[188:191], v154 offset:32768
	ds_read_b128 v[192:195], v154 offset:33792
	ds_read_b128 v[196:199], v154 offset:34816
	ds_read_b128 v[200:203], v154 offset:35840
	ds_read_b128 v[204:207], v154 offset:36864
	ds_read_b128 v[208:211], v154 offset:37888
	ds_read_b128 v[226:229], v154 offset:38912
	ds_read_b128 v[230:233], v154 offset:39936
	global_load_lds_dwordx4 v[240:241], off
	v_lshl_add_u64 v[240:241], s[24:25], 0, v[134:135]
	s_mov_b32 m0, s39
	s_nop 0
	global_load_lds_dwordx4 v[240:241], off
	s_waitcnt vmcnt(8)
	s_waitcnt lgkmcnt(0)
	s_barrier
	v_mfma_f32_16x16x32_bf16 v[128:131], v[142:145], v[188:191], v[128:131]
	v_mfma_f32_16x16x32_bf16 v[120:123], v[160:163], v[188:191], v[120:123]
	v_mfma_f32_16x16x32_bf16 v[112:115], v[142:145], v[196:199], v[112:115]
	v_mfma_f32_16x16x32_bf16 v[104:107], v[160:163], v[196:199], v[104:107]
	v_mfma_f32_16x16x32_bf16 v[96:99], v[142:145], v[204:207], v[96:99]
	v_mfma_f32_16x16x32_bf16 v[88:91], v[160:163], v[204:207], v[88:91]
	v_mfma_f32_16x16x32_bf16 v[80:83], v[142:145], v[226:229], v[80:83]
	v_mfma_f32_16x16x32_bf16 v[72:75], v[160:163], v[226:229], v[72:75]
	v_mfma_f32_16x16x32_bf16 v[128:131], v[156:159], v[192:195], v[128:131]
	v_mfma_f32_16x16x32_bf16 v[120:123], v[164:167], v[192:195], v[120:123]
	v_mfma_f32_16x16x32_bf16 v[112:115], v[156:159], v[200:203], v[112:115]
	v_mfma_f32_16x16x32_bf16 v[104:107], v[164:167], v[200:203], v[104:107]
	v_mfma_f32_16x16x32_bf16 v[96:99], v[156:159], v[208:211], v[96:99]
	v_mfma_f32_16x16x32_bf16 v[88:91], v[164:167], v[208:211], v[88:91]
	v_mfma_f32_16x16x32_bf16 v[80:83], v[156:159], v[230:233], v[80:83]
	v_mfma_f32_16x16x32_bf16 v[72:75], v[164:167], v[230:233], v[72:75]
	v_mfma_f32_16x16x32_bf16 v[124:127], v[172:175], v[188:191], v[124:127]
	v_mfma_f32_16x16x32_bf16 v[116:119], v[180:183], v[188:191], v[116:119]
	v_mfma_f32_16x16x32_bf16 v[108:111], v[172:175], v[196:199], v[108:111]
	v_mfma_f32_16x16x32_bf16 v[100:103], v[180:183], v[196:199], v[100:103]
	v_mfma_f32_16x16x32_bf16 v[92:95], v[172:175], v[204:207], v[92:95]
	v_mfma_f32_16x16x32_bf16 v[84:87], v[180:183], v[204:207], v[84:87]
	v_mfma_f32_16x16x32_bf16 v[76:79], v[172:175], v[226:229], v[76:79]
	v_mfma_f32_16x16x32_bf16 v[68:71], v[180:183], v[226:229], v[68:71]
	v_mfma_f32_16x16x32_bf16 v[124:127], v[176:179], v[192:195], v[124:127]
	v_mfma_f32_16x16x32_bf16 v[116:119], v[184:187], v[192:195], v[116:119]
	v_mfma_f32_16x16x32_bf16 v[108:111], v[176:179], v[200:203], v[108:111]
	v_mfma_f32_16x16x32_bf16 v[100:103], v[184:187], v[200:203], v[100:103]
	v_mfma_f32_16x16x32_bf16 v[92:95], v[176:179], v[208:211], v[92:95]
	v_mfma_f32_16x16x32_bf16 v[84:87], v[184:187], v[208:211], v[84:87]
	v_mfma_f32_16x16x32_bf16 v[76:79], v[176:179], v[230:233], v[76:79]
	v_mfma_f32_16x16x32_bf16 v[68:71], v[184:187], v[230:233], v[68:71]
	s_barrier
; #define PG8_STAGE(bufoff, gbase, voff) do { _Pragma("unroll") for (int _i = 0; _i < 2; ++_i) \
;         __builtin_amdgcn_global_load_lds((const unsigned*)((const char*)(gbase) + (voff)[_i]), (PG8_LAS unsigned*)(lds + (bufoff) + ldsw + _i * 8192), 16, 0, 0); } while (0)
; #define PG8_LDA(dst, b, h) do { _Pragma("unroll") for (int m = 0; m < 4; ++m) _Pragma("unroll") for (int k = 0; k < 2; ++k) dst[m][k] = *(const PG8_LAS bf16x8*)(lds + PG8_SA(b, h) + aoffk[k] + m * 2048); } while (0)
; #define PG8_MMA(ai, bj, At, Bt) do { __builtin_amdgcn_s_setprio(1); _Pragma("unroll") for (int m = 0; m < 4; ++m) _Pragma("unroll") for (int n = 0; n < 2; ++n) _Pragma("unroll") for (int k = 0; k < 2; ++k) \
;         acc[ai][bj][m][n] = __builtin_amdgcn_mfma_f32_16x16x32_bf16(Bt[n][k], At[m][k], acc[ai][bj][m][n], 0, 0, 0); __builtin_amdgcn_s_setprio(0); } while (0)
; #define PG8_WAIT_V(n) asm volatile("s_waitcnt vmcnt(" #n ")" ::: "memory")
; #define PG8_WAIT_L(n) asm volatile("s_waitcnt lgkmcnt(" #n ")" ::: "memory")
; #define PG8_BAR __builtin_amdgcn_s_barrier()
; #define PG8_SCHED __builtin_amdgcn_sched_barrier(0)
; template <class Epi, class Sched, bool ALIGN_EPI = false, bool SP2 = false>
; __device__ __forceinline__ void gemm_phase(PG8_LAS unsigned char* lds, const Gemm g, const Sched& S, const Epi& E) {
;     ...
;         for (int t = 0; t < nt; t += 2) {
;             const bool last = (t == nt - 2);
;             const char* a1 = cA + (size_t)(t + 1) * kstep;
;             const char* a2 = last ? nA : cA + (size_t)(t + 2) * kstep; const char* b2 = last ? nB : cB + (size_t)(t + 2) * kstep;
;             const char* a3 = a2 + kstep; const char* b3 = b2 + kstep;
;     ...
;             PG8_LDA(At, 1, 1); PG8_STAGE(PG8_SB(1, 0), b3, voffB); PG8_STAGE(PG8_SB(1, 1), b3 + hstepB, voffB); PG8_STAGE(PG8_SA(1, 0), a3, voffA);
;             PG8_WAIT_V(8); PG8_WAIT_L(0); PG8_BAR; PG8_MMA(1, 0, At, B0); PG8_MMA(1, 1, At, B1); PG8_BAR; PG8_SCHED;
	s_add_i32 s24, s47, s34
	v_lshl_add_u64 v[212:213], v[212:213], 0, s[56:57]
	s_mov_b32 m0, s24
	ds_read_b128 v[188:191], v154 offset:49152
	ds_read_b128 v[192:195], v154 offset:50176
	ds_read_b128 v[196:199], v154 offset:51200
	ds_read_b128 v[200:203], v154 offset:52224
	ds_read_b128 v[204:207], v154 offset:53248
	ds_read_b128 v[208:211], v154 offset:54272
	ds_read_b128 v[226:229], v154 offset:55296
	ds_read_b128 v[230:233], v154 offset:56320
	global_load_lds_dwordx4 v[212:213], off
	s_add_i32 m0, s24, 0x2000
	s_add_u32 s22, s22, 0x80080
	v_lshl_add_u64 v[212:213], v[234:235], 0, s[56:57]
	s_addc_u32 s23, s23, 0
	s_add_i32 s24, s48, s34
	global_load_lds_dwordx4 v[212:213], off
	v_lshl_add_u64 v[212:213], s[22:23], 0, v[2:3]
	s_mov_b32 m0, s24
	s_nop 0
	global_load_lds_dwordx4 v[212:213], off
	v_lshl_add_u64 v[212:213], s[22:23], 0, v[132:133]
	s_add_i32 m0, s24, 0x2000
	s_nop 0
	global_load_lds_dwordx4 v[212:213], off
	v_lshl_add_u64 v[212:213], v[236:237], 0, s[56:57]
	s_mov_b32 m0, s40
	s_nop 0
	global_load_lds_dwordx4 v[212:213], off
	v_lshl_add_u64 v[212:213], v[238:239], 0, s[56:57]
	s_mov_b32 m0, s41
	s_nop 0
	global_load_lds_dwordx4 v[212:213], off
	s_waitcnt vmcnt(8)
	s_waitcnt lgkmcnt(0)
	s_barrier
	v_mfma_f32_16x16x32_bf16 v[64:67], v[142:145], v[188:191], v[64:67]
	v_mfma_f32_16x16x32_bf16 v[56:59], v[160:163], v[188:191], v[56:59]
	v_mfma_f32_16x16x32_bf16 v[48:51], v[142:145], v[196:199], v[48:51]
	v_mfma_f32_16x16x32_bf16 v[40:43], v[160:163], v[196:199], v[40:43]
	v_mfma_f32_16x16x32_bf16 v[32:35], v[142:145], v[204:207], v[32:35]
	v_mfma_f32_16x16x32_bf16 v[24:27], v[160:163], v[204:207], v[24:27]
	v_mfma_f32_16x16x32_bf16 v[16:19], v[142:145], v[226:229], v[16:19]
	v_mfma_f32_16x16x32_bf16 v[8:11], v[160:163], v[226:229], v[8:11]
	v_mfma_f32_16x16x32_bf16 v[64:67], v[156:159], v[192:195], v[64:67]
	v_mfma_f32_16x16x32_bf16 v[56:59], v[164:167], v[192:195], v[56:59]
	v_mfma_f32_16x16x32_bf16 v[48:51], v[156:159], v[200:203], v[48:51]
	v_mfma_f32_16x16x32_bf16 v[40:43], v[164:167], v[200:203], v[40:43]
	v_mfma_f32_16x16x32_bf16 v[32:35], v[156:159], v[208:211], v[32:35]
	v_mfma_f32_16x16x32_bf16 v[24:27], v[164:167], v[208:211], v[24:27]
	v_mfma_f32_16x16x32_bf16 v[16:19], v[156:159], v[230:233], v[16:19]
	v_mfma_f32_16x16x32_bf16 v[8:11], v[164:167], v[230:233], v[8:11]
	v_mfma_f32_16x16x32_bf16 v[60:63], v[172:175], v[188:191], v[60:63]
	v_mfma_f32_16x16x32_bf16 v[52:55], v[180:183], v[188:191], v[52:55]
	v_mfma_f32_16x16x32_bf16 v[44:47], v[172:175], v[196:199], v[44:47]
	v_mfma_f32_16x16x32_bf16 v[36:39], v[180:183], v[196:199], v[36:39]
	v_mfma_f32_16x16x32_bf16 v[28:31], v[172:175], v[204:207], v[28:31]
	v_mfma_f32_16x16x32_bf16 v[20:23], v[180:183], v[204:207], v[20:23]
	v_mfma_f32_16x16x32_bf16 v[12:15], v[172:175], v[226:229], v[12:15]
	v_mfma_f32_16x16x32_bf16 v[4:7], v[180:183], v[226:229], v[4:7]
	v_mfma_f32_16x16x32_bf16 v[60:63], v[176:179], v[192:195], v[60:63]
	v_mfma_f32_16x16x32_bf16 v[52:55], v[184:187], v[192:195], v[52:55]
	v_mfma_f32_16x16x32_bf16 v[44:47], v[176:179], v[200:203], v[44:47]
	v_mfma_f32_16x16x32_bf16 v[36:39], v[184:187], v[200:203], v[36:39]
	v_mfma_f32_16x16x32_bf16 v[28:31], v[176:179], v[208:211], v[28:31]
	v_mfma_f32_16x16x32_bf16 v[20:23], v[184:187], v[208:211], v[20:23]
	v_mfma_f32_16x16x32_bf16 v[12:15], v[176:179], v[230:233], v[12:15]
	v_mfma_f32_16x16x32_bf16 v[4:7], v[184:187], v[230:233], v[4:7]
	s_barrier
	s_add_i32 s46, s46, 2
	s_add_u32 s20, s20, 0x100
	s_addc_u32 s21, s21, 0
	s_add_u32 s44, s44, 0x100
	s_addc_u32 s45, s45, 0
	s_cmp_gt_u32 s46, 29
	s_cbranch_scc0 .LBB0_296
	s_branch .Lgemm_after_0

; #define PG8_BAR __builtin_amdgcn_s_barrier()
; template <class Epi, class Sched, bool ALIGN_EPI = false, bool SP2 = false>
; __device__ __forceinline__ void gemm_phase(PG8_LAS unsigned char* lds, const Gemm g, const Sched& S, const Epi& E) {
;     ...
;         if constexpr (ALIGN_EPI) { if (wr == 0) PG8_BAR; }
.Lgemm_after_0:
	s_and_b64 vcc, exec, s[6:7]
	s_cbranch_vccz .LBB0_299
	s_barrier

; #define PG8_STAGE(bufoff, gbase, voff) do { _Pragma("unroll") for (int _i = 0; _i < 2; ++_i) \
;         __builtin_amdgcn_global_load_lds((const unsigned*)((const char*)(gbase) + (voff)[_i]), (PG8_LAS unsigned*)(lds + (bufoff) + ldsw + _i * 8192), 16, 0, 0); } while (0)
; #define PG8_LDA(dst, b, h) do { _Pragma("unroll") for (int m = 0; m < 4; ++m) _Pragma("unroll") for (int k = 0; k < 2; ++k) dst[m][k] = *(const PG8_LAS bf16x8*)(lds + PG8_SA(b, h) + aoffk[k] + m * 2048); } while (0)
; #define PG8_WAIT_V(n) asm volatile("s_waitcnt vmcnt(" #n ")" ::: "memory")
; #define PG8_BAR __builtin_amdgcn_s_barrier()
; template <class Epi, class Sched, bool ALIGN_EPI = false, bool SP2 = false>
; __device__ __forceinline__ void gemm_phase(PG8_LAS unsigned char* lds, const Gemm g, const Sched& S, const Epi& E) {
;     ...
;     f32x4 acc[2][2][4][2];
; #pragma unroll
;     for (int a = 0; a < 2; ++a)
; #pragma unroll
;         for (int b = 0; b < 2; ++b)
; #pragma unroll
;             for (int m = 0; m < 4; ++m)
; #pragma unroll
;                 for (int n = 0; n < 2; ++n) acc[a][b][m][n] = (f32x4){0.f, 0.f, 0.f, 0.f};
;     ...
;         const bool has_next = S.next(ui + 1, nxt);
;         const char* nA = has_next ? (const char*)g.A + (size_t)nxt.pm * tstepA + (size_t)nxt.kt0 * kstep : cA; const char* nB = has_next ? (const char*)g.Bt + (size_t)nxt.pn * tstepB + (size_t)nxt.kt0 * kstep : cB;
;         const int nt = cur.nt;
;         for (int t = 0; t < nt; t += 2) {
;             const bool last = (t == nt - 2);
;             const char* a1 = cA + (size_t)(t + 1) * kstep;
;             const char* a2 = last ? nA : cA + (size_t)(t + 2) * kstep; const char* b2 = last ? nB : cB + (size_t)(t + 2) * kstep;
;             const char* a3 = a2 + kstep; const char* b3 = b2 + kstep;
;             if (last && has_next) S.a_ready(nxt);
;             if constexpr (SP2) {
;             PG8_LDB(B0, 0, 0); PG8_LDB(B1, 0, 1); PG8_SCHED; PG8_LDA(At, 0, 0); PG8_STAGE(PG8_SA(1, 1), a1 + hstepA, voffA);
;             PG8_WAIT_V(8); PG8_WAIT_L(0); PG8_BAR; PG8_MMA(0, 0, At, B0); PG8_MMA(0, 1, At, B1); PG8_BAR; PG8_SCHED;
;             PG8_LDA(At, 0, 1); PG8_STAGE(PG8_SB(0, 0), b2, voffB); PG8_STAGE(PG8_SB(0, 1), b2 + hstepB, voffB); PG8_STAGE(PG8_SA(0, 0), a2, voffA);
;             PG8_WAIT_V(8); PG8_WAIT_L(0); PG8_BAR; PG8_MMA(1, 0, At, B0); PG8_MMA(1, 1, At, B1); PG8_BAR; PG8_SCHED;
.LBB0_429:
	s_add_i32 s9, s44, -2
	s_add_u32 s49, s16, 0x100
	s_addc_u32 s50, s17, 0
	s_mov_b32 s18, 0
	v_readlane_b32 s54, v253, 28
	v_readlane_b32 s55, v253, 29
	v_readlane_b32 s56, v253, 30
	v_readlane_b32 s57, v253, 31
	s_mov_b64 s[58:59], 0x80
.Lgemm_first_1:
	s_add_i32 s51, s18, 2
	s_add_u32 s16, s14, 0x100
	s_addc_u32 s17, s15, 0
	s_add_i32 s52, 0, 0x10000
	s_cmp_eq_u32 s9, s18
	v_add_u32_e32 v142, s52, v145
	s_cselect_b32 s21, s11, s17
	s_cselect_b32 s20, s10, s16
	v_add_u32_e32 v143, s52, v146
	ds_read_b128 v[150:153], v142
	ds_read_b128 v[154:157], v143
	v_add_u32_e32 v142, s54, v145
	s_cselect_b32 s19, s13, s50
	s_cselect_b32 s18, s12, s49
	s_add_i32 s53, 0, 0x14000
	v_add_u32_e32 v143, s54, v146
	ds_read_b128 v[158:161], v142
	ds_read_b128 v[162:165], v143
	v_add_u32_e32 v142, s53, v145
	v_add_u32_e32 v143, s53, v146
	ds_read_b128 v[172:175], v142
	ds_read_b128 v[176:179], v143
	v_add_u32_e32 v142, s55, v145
	v_add_u32_e32 v143, s55, v146
	ds_read_b128 v[180:183], v142
	ds_read_b128 v[184:187], v143
	v_lshl_add_u64 v[142:143], s[14:15], 0, v[138:139]
	s_add_i32 m0, s28, 0xc000
	ds_read_b128 v[188:191], v148
	ds_read_b128 v[192:195], v148 offset:1024
	ds_read_b128 v[196:199], v148 offset:2048
	ds_read_b128 v[200:203], v148 offset:3072
	ds_read_b128 v[204:207], v148 offset:4096
	ds_read_b128 v[208:211], v148 offset:5120
	ds_read_b128 v[226:229], v148 offset:6144
	ds_read_b128 v[230:233], v148 offset:7168
	global_load_lds_dwordx4 v[142:143], off
	v_lshl_add_u64 v[142:143], s[14:15], 0, v[140:141]
	s_add_i32 m0, s28, 0xe000
	s_nop 0
	global_load_lds_dwordx4 v[142:143], off
	s_waitcnt vmcnt(8)
	s_waitcnt lgkmcnt(0)
	s_barrier
	v_mfma_f32_16x16x32_bf16 v[128:131], v[150:153], v[188:191], 0
	v_mfma_f32_16x16x32_bf16 v[124:127], v[158:161], v[188:191], 0
	v_mfma_f32_16x16x32_bf16 v[120:123], v[150:153], v[196:199], 0
	v_mfma_f32_16x16x32_bf16 v[112:115], v[158:161], v[196:199], 0
	v_mfma_f32_16x16x32_bf16 v[104:107], v[150:153], v[204:207], 0
	v_mfma_f32_16x16x32_bf16 v[96:99], v[158:161], v[204:207], 0
	v_mfma_f32_16x16x32_bf16 v[88:91], v[150:153], v[226:229], 0
	v_mfma_f32_16x16x32_bf16 v[80:83], v[158:161], v[226:229], 0
	v_mfma_f32_16x16x32_bf16 v[128:131], v[154:157], v[192:195], v[128:131]
	v_mfma_f32_16x16x32_bf16 v[124:127], v[162:165], v[192:195], v[124:127]
	v_mfma_f32_16x16x32_bf16 v[120:123], v[154:157], v[200:203], v[120:123]
	v_mfma_f32_16x16x32_bf16 v[112:115], v[162:165], v[200:203], v[112:115]
	v_mfma_f32_16x16x32_bf16 v[104:107], v[154:157], v[208:211], v[104:107]
	v_mfma_f32_16x16x32_bf16 v[96:99], v[162:165], v[208:211], v[96:99]
	v_mfma_f32_16x16x32_bf16 v[88:91], v[154:157], v[230:233], v[88:91]
	v_mfma_f32_16x16x32_bf16 v[80:83], v[162:165], v[230:233], v[80:83]
	v_mfma_f32_16x16x32_bf16 v[116:119], v[172:175], v[188:191], 0
	v_mfma_f32_16x16x32_bf16 v[108:111], v[180:183], v[188:191], 0
	v_mfma_f32_16x16x32_bf16 v[100:103], v[172:175], v[196:199], 0
	v_mfma_f32_16x16x32_bf16 v[92:95], v[180:183], v[196:199], 0
	v_mfma_f32_16x16x32_bf16 v[84:87], v[172:175], v[204:207], 0
	v_mfma_f32_16x16x32_bf16 v[76:79], v[180:183], v[204:207], 0
	v_mfma_f32_16x16x32_bf16 v[72:75], v[172:175], v[226:229], 0
	v_mfma_f32_16x16x32_bf16 v[68:71], v[180:183], v[226:229], 0
	v_mfma_f32_16x16x32_bf16 v[116:119], v[176:179], v[192:195], v[116:119]
	v_mfma_f32_16x16x32_bf16 v[108:111], v[184:187], v[192:195], v[108:111]
	v_mfma_f32_16x16x32_bf16 v[100:103], v[176:179], v[200:203], v[100:103]
	v_mfma_f32_16x16x32_bf16 v[92:95], v[184:187], v[200:203], v[92:95]
	v_mfma_f32_16x16x32_bf16 v[84:87], v[176:179], v[208:211], v[84:87]
	v_mfma_f32_16x16x32_bf16 v[76:79], v[184:187], v[208:211], v[76:79]
	v_mfma_f32_16x16x32_bf16 v[72:75], v[176:179], v[230:233], v[72:75]
	v_mfma_f32_16x16x32_bf16 v[68:71], v[184:187], v[230:233], v[68:71]
	s_barrier
	s_add_i32 s14, s52, s27
	v_lshl_add_u64 v[142:143], s[18:19], 0, v[2:3]
	s_mov_b32 m0, s14
	ds_read_b128 v[188:191], v148 offset:16384
	ds_read_b128 v[192:195], v148 offset:17408
	ds_read_b128 v[196:199], v148 offset:18432
	ds_read_b128 v[200:203], v148 offset:19456
	ds_read_b128 v[204:207], v148 offset:20480
	ds_read_b128 v[208:211], v148 offset:21504
	ds_read_b128 v[226:229], v148 offset:22528
	ds_read_b128 v[230:233], v148 offset:23552
	global_load_lds_dwordx4 v[142:143], off
	s_add_i32 m0, s14, 0x2000
	s_add_u32 s14, s18, 0x160000
	v_lshl_add_u64 v[166:167], s[18:19], 0, v[136:137]
	s_addc_u32 s15, s19, 0
	s_add_i32 s52, s53, s27
	global_load_lds_dwordx4 v[166:167], off
	v_lshl_add_u64 v[212:213], s[14:15], 0, v[2:3]
	s_mov_b32 m0, s52
	v_lshl_add_u64 v[234:235], s[20:21], 0, v[134:135]
	global_load_lds_dwordx4 v[212:213], off
	v_lshl_add_u64 v[212:213], s[14:15], 0, v[136:137]
	s_add_i32 m0, s52, 0x2000
	s_nop 0
	global_load_lds_dwordx4 v[212:213], off
	v_lshl_add_u64 v[212:213], s[20:21], 0, v[132:133]
	s_mov_b32 m0, s28
	s_nop 0
	global_load_lds_dwordx4 v[212:213], off
	s_mov_b32 m0, s29
	s_nop 0
	global_load_lds_dwordx4 v[234:235], off
	s_waitcnt vmcnt(8)
	s_waitcnt lgkmcnt(0)
	s_barrier
; #define PG8_STAGE(bufoff, gbase, voff) do { _Pragma("unroll") for (int _i = 0; _i < 2; ++_i) \
;         __builtin_amdgcn_global_load_lds((const unsigned*)((const char*)(gbase) + (voff)[_i]), (PG8_LAS unsigned*)(lds + (bufoff) + ldsw + _i * 8192), 16, 0, 0); } while (0)
; #define PG8_LDA(dst, b, h) do { _Pragma("unroll") for (int m = 0; m < 4; ++m) _Pragma("unroll") for (int k = 0; k < 2; ++k) dst[m][k] = *(const PG8_LAS bf16x8*)(lds + PG8_SA(b, h) + aoffk[k] + m * 2048); } while (0)
; #define PG8_LDB(dst, b, h) do { _Pragma("unroll") for (int n = 0; n < 2; ++n) _Pragma("unroll") for (int k = 0; k < 2; ++k) dst[n][k] = *(const PG8_LAS bf16x8*)(lds + PG8_SB(b, h) + boffk[k] + n * 2048); } while (0)
; #define PG8_MMA(ai, bj, At, Bt) do { __builtin_amdgcn_s_setprio(1); _Pragma("unroll") for (int m = 0; m < 4; ++m) _Pragma("unroll") for (int n = 0; n < 2; ++n) _Pragma("unroll") for (int k = 0; k < 2; ++k) \
;         acc[ai][bj][m][n] = __builtin_amdgcn_mfma_f32_16x16x32_bf16(Bt[n][k], At[m][k], acc[ai][bj][m][n], 0, 0, 0); __builtin_amdgcn_s_setprio(0); } while (0)
; #define PG8_WAIT_V(n) asm volatile("s_waitcnt vmcnt(" #n ")" ::: "memory")
; #define PG8_WAIT_L(n) asm volatile("s_waitcnt lgkmcnt(" #n ")" ::: "memory")
; #define PG8_BAR __builtin_amdgcn_s_barrier()
; #define PG8_SCHED __builtin_amdgcn_sched_barrier(0)
; template <class Epi, class Sched, bool ALIGN_EPI = false, bool SP2 = false>
; __device__ __forceinline__ void gemm_phase(PG8_LAS unsigned char* lds, const Gemm g, const Sched& S, const Epi& E) {
;     ...
;             PG8_LDA(At, 0, 1); PG8_STAGE(PG8_SB(0, 0), b2, voffB); PG8_STAGE(PG8_SB(0, 1), b2 + hstepB, voffB); PG8_STAGE(PG8_SA(0, 0), a2, voffA);
;             PG8_WAIT_V(8); PG8_WAIT_L(0); PG8_BAR; PG8_MMA(1, 0, At, B0); PG8_MMA(1, 1, At, B1); PG8_BAR; PG8_SCHED;
;             PG8_LDB(B0, 1, 0); PG8_LDB(B1, 1, 1); PG8_SCHED; PG8_LDA(At, 1, 0); PG8_STAGE(PG8_SA(0, 1), a2 + hstepA, voffA);
;             PG8_WAIT_V(8); PG8_WAIT_L(0); PG8_BAR; PG8_MMA(0, 0, At, B0); PG8_MMA(0, 1, At, B1); PG8_BAR; PG8_SCHED;
	v_mfma_f32_16x16x32_bf16 v[64:67], v[150:153], v[188:191], 0
	v_mfma_f32_16x16x32_bf16 v[60:63], v[158:161], v[188:191], 0
	v_mfma_f32_16x16x32_bf16 v[56:59], v[150:153], v[196:199], 0
	v_mfma_f32_16x16x32_bf16 v[48:51], v[158:161], v[196:199], 0
	v_mfma_f32_16x16x32_bf16 v[40:43], v[150:153], v[204:207], 0
	v_mfma_f32_16x16x32_bf16 v[32:35], v[158:161], v[204:207], 0
	v_mfma_f32_16x16x32_bf16 v[24:27], v[150:153], v[226:229], 0
	v_mfma_f32_16x16x32_bf16 v[16:19], v[158:161], v[226:229], 0
	v_mfma_f32_16x16x32_bf16 v[64:67], v[154:157], v[192:195], v[64:67]
	v_mfma_f32_16x16x32_bf16 v[60:63], v[162:165], v[192:195], v[60:63]
	v_mfma_f32_16x16x32_bf16 v[56:59], v[154:157], v[200:203], v[56:59]
	v_mfma_f32_16x16x32_bf16 v[48:51], v[162:165], v[200:203], v[48:51]
	v_mfma_f32_16x16x32_bf16 v[40:43], v[154:157], v[208:211], v[40:43]
	v_mfma_f32_16x16x32_bf16 v[32:35], v[162:165], v[208:211], v[32:35]
	v_mfma_f32_16x16x32_bf16 v[24:27], v[154:157], v[230:233], v[24:27]
	v_mfma_f32_16x16x32_bf16 v[16:19], v[162:165], v[230:233], v[16:19]
	v_mfma_f32_16x16x32_bf16 v[52:55], v[172:175], v[188:191], 0
	v_mfma_f32_16x16x32_bf16 v[44:47], v[180:183], v[188:191], 0
	v_mfma_f32_16x16x32_bf16 v[36:39], v[172:175], v[196:199], 0
	v_mfma_f32_16x16x32_bf16 v[28:31], v[180:183], v[196:199], 0
	v_mfma_f32_16x16x32_bf16 v[20:23], v[172:175], v[204:207], 0
	v_mfma_f32_16x16x32_bf16 v[12:15], v[180:183], v[204:207], 0
	v_mfma_f32_16x16x32_bf16 v[8:11], v[172:175], v[226:229], 0
	v_mfma_f32_16x16x32_bf16 v[4:7], v[180:183], v[226:229], 0
	v_mfma_f32_16x16x32_bf16 v[52:55], v[176:179], v[192:195], v[52:55]
	v_mfma_f32_16x16x32_bf16 v[44:47], v[184:187], v[192:195], v[44:47]
	v_mfma_f32_16x16x32_bf16 v[36:39], v[176:179], v[200:203], v[36:39]
	v_mfma_f32_16x16x32_bf16 v[28:31], v[184:187], v[200:203], v[28:31]
	v_mfma_f32_16x16x32_bf16 v[20:23], v[176:179], v[208:211], v[20:23]
	v_mfma_f32_16x16x32_bf16 v[12:15], v[184:187], v[208:211], v[12:15]
	v_mfma_f32_16x16x32_bf16 v[8:11], v[176:179], v[230:233], v[8:11]
	v_mfma_f32_16x16x32_bf16 v[4:7], v[184:187], v[230:233], v[4:7]
	s_barrier
	s_add_i32 s52, 0, 0x18000
	v_add_u32_e32 v149, s52, v145
	v_add_u32_e32 v154, s52, v146
	ds_read_b128 v[150:153], v149
	ds_read_b128 v[154:157], v154
	v_add_u32_e32 v149, s56, v145
	v_add_u32_e32 v162, s56, v146
	s_add_i32 s53, 0, 0x1c000
	ds_read_b128 v[158:161], v149
	ds_read_b128 v[162:165], v162
	v_add_u32_e32 v149, s53, v145
	v_add_u32_e32 v168, s53, v146
	ds_read_b128 v[172:175], v149
	ds_read_b128 v[176:179], v168
	v_add_u32_e32 v149, s57, v145
	v_add_u32_e32 v168, s57, v146
	ds_read_b128 v[180:183], v149
	ds_read_b128 v[184:187], v168
	s_add_u32 s14, s20, 0x160000
	s_addc_u32 s15, s21, 0
	s_mov_b32 m0, s30
	v_lshl_add_u64 v[236:237], s[14:15], 0, v[132:133]
	ds_read_b128 v[188:191], v148 offset:32768
	ds_read_b128 v[192:195], v148 offset:33792
	ds_read_b128 v[196:199], v148 offset:34816
	ds_read_b128 v[200:203], v148 offset:35840
	ds_read_b128 v[204:207], v148 offset:36864
	ds_read_b128 v[208:211], v148 offset:37888
	ds_read_b128 v[226:229], v148 offset:38912
	ds_read_b128 v[230:233], v148 offset:39936
	global_load_lds_dwordx4 v[236:237], off
	v_lshl_add_u64 v[236:237], s[14:15], 0, v[134:135]
	s_mov_b32 m0, s31
	s_nop 0
	global_load_lds_dwordx4 v[236:237], off
	s_waitcnt vmcnt(8)
	s_waitcnt lgkmcnt(0)
	s_barrier
	v_mfma_f32_16x16x32_bf16 v[128:131], v[150:153], v[188:191], v[128:131]
	v_mfma_f32_16x16x32_bf16 v[124:127], v[158:161], v[188:191], v[124:127]
	v_mfma_f32_16x16x32_bf16 v[120:123], v[150:153], v[196:199], v[120:123]
	v_mfma_f32_16x16x32_bf16 v[112:115], v[158:161], v[196:199], v[112:115]
	v_mfma_f32_16x16x32_bf16 v[104:107], v[150:153], v[204:207], v[104:107]
	v_mfma_f32_16x16x32_bf16 v[96:99], v[158:161], v[204:207], v[96:99]
	v_mfma_f32_16x16x32_bf16 v[88:91], v[150:153], v[226:229], v[88:91]
	v_mfma_f32_16x16x32_bf16 v[80:83], v[158:161], v[226:229], v[80:83]
	v_mfma_f32_16x16x32_bf16 v[128:131], v[154:157], v[192:195], v[128:131]
	v_mfma_f32_16x16x32_bf16 v[124:127], v[162:165], v[192:195], v[124:127]
	v_mfma_f32_16x16x32_bf16 v[120:123], v[154:157], v[200:203], v[120:123]
	v_mfma_f32_16x16x32_bf16 v[112:115], v[162:165], v[200:203], v[112:115]
	v_mfma_f32_16x16x32_bf16 v[104:107], v[154:157], v[208:211], v[104:107]
	v_mfma_f32_16x16x32_bf16 v[96:99], v[162:165], v[208:211], v[96:99]
	v_mfma_f32_16x16x32_bf16 v[88:91], v[154:157], v[230:233], v[88:91]
	v_mfma_f32_16x16x32_bf16 v[80:83], v[162:165], v[230:233], v[80:83]
	v_mfma_f32_16x16x32_bf16 v[116:119], v[172:175], v[188:191], v[116:119]
	v_mfma_f32_16x16x32_bf16 v[108:111], v[180:183], v[188:191], v[108:111]
	v_mfma_f32_16x16x32_bf16 v[100:103], v[172:175], v[196:199], v[100:103]
	v_mfma_f32_16x16x32_bf16 v[92:95], v[180:183], v[196:199], v[92:95]
	v_mfma_f32_16x16x32_bf16 v[84:87], v[172:175], v[204:207], v[84:87]
	v_mfma_f32_16x16x32_bf16 v[76:79], v[180:183], v[204:207], v[76:79]
	v_mfma_f32_16x16x32_bf16 v[72:75], v[172:175], v[226:229], v[72:75]
	v_mfma_f32_16x16x32_bf16 v[68:71], v[180:183], v[226:229], v[68:71]
	v_mfma_f32_16x16x32_bf16 v[116:119], v[176:179], v[192:195], v[116:119]
	v_mfma_f32_16x16x32_bf16 v[108:111], v[184:187], v[192:195], v[108:111]
	v_mfma_f32_16x16x32_bf16 v[100:103], v[176:179], v[200:203], v[100:103]
	v_mfma_f32_16x16x32_bf16 v[92:95], v[184:187], v[200:203], v[92:95]
	v_mfma_f32_16x16x32_bf16 v[84:87], v[176:179], v[208:211], v[84:87]
	v_mfma_f32_16x16x32_bf16 v[76:79], v[184:187], v[208:211], v[76:79]
	v_mfma_f32_16x16x32_bf16 v[72:75], v[176:179], v[230:233], v[72:75]
	v_mfma_f32_16x16x32_bf16 v[68:71], v[184:187], v[230:233], v[68:71]
	s_barrier
; #define PG8_STAGE(bufoff, gbase, voff) do { _Pragma("unroll") for (int _i = 0; _i < 2; ++_i) \
;         __builtin_amdgcn_global_load_lds((const unsigned*)((const char*)(gbase) + (voff)[_i]), (PG8_LAS unsigned*)(lds + (bufoff) + ldsw + _i * 8192), 16, 0, 0); } while (0)
; #define PG8_LDA(dst, b, h) do { _Pragma("unroll") for (int m = 0; m < 4; ++m) _Pragma("unroll") for (int k = 0; k < 2; ++k) dst[m][k] = *(const PG8_LAS bf16x8*)(lds + PG8_SA(b, h) + aoffk[k] + m * 2048); } while (0)
; #define PG8_MMA(ai, bj, At, Bt) do { __builtin_amdgcn_s_setprio(1); _Pragma("unroll") for (int m = 0; m < 4; ++m) _Pragma("unroll") for (int n = 0; n < 2; ++n) _Pragma("unroll") for (int k = 0; k < 2; ++k) \
;         acc[ai][bj][m][n] = __builtin_amdgcn_mfma_f32_16x16x32_bf16(Bt[n][k], At[m][k], acc[ai][bj][m][n], 0, 0, 0); __builtin_amdgcn_s_setprio(0); } while (0)
; #define PG8_WAIT_V(n) asm volatile("s_waitcnt vmcnt(" #n ")" ::: "memory")
; #define PG8_WAIT_L(n) asm volatile("s_waitcnt lgkmcnt(" #n ")" ::: "memory")
; #define PG8_BAR __builtin_amdgcn_s_barrier()
; #define PG8_SCHED __builtin_amdgcn_sched_barrier(0)
; template <class Epi, class Sched, bool ALIGN_EPI = false, bool SP2 = false>
; __device__ __forceinline__ void gemm_phase(PG8_LAS unsigned char* lds, const Gemm g, const Sched& S, const Epi& E) {
;     ...
;         for (int t = 0; t < nt; t += 2) {
;             const bool last = (t == nt - 2);
;             const char* a1 = cA + (size_t)(t + 1) * kstep;
;             const char* a2 = last ? nA : cA + (size_t)(t + 2) * kstep; const char* b2 = last ? nB : cB + (size_t)(t + 2) * kstep;
;             const char* a3 = a2 + kstep; const char* b3 = b2 + kstep;
;     ...
;             PG8_LDA(At, 1, 1); PG8_STAGE(PG8_SB(1, 0), b3, voffB); PG8_STAGE(PG8_SB(1, 1), b3 + hstepB, voffB); PG8_STAGE(PG8_SA(1, 0), a3, voffA);
;             PG8_WAIT_V(8); PG8_WAIT_L(0); PG8_BAR; PG8_MMA(1, 0, At, B0); PG8_MMA(1, 1, At, B1); PG8_BAR; PG8_SCHED;
	s_add_i32 s14, s52, s27
	v_lshl_add_u64 v[142:143], v[142:143], 0, s[58:59]
	s_mov_b32 m0, s14
	ds_read_b128 v[188:191], v148 offset:49152
	ds_read_b128 v[192:195], v148 offset:50176
	ds_read_b128 v[196:199], v148 offset:51200
	ds_read_b128 v[200:203], v148 offset:52224
	ds_read_b128 v[204:207], v148 offset:53248
	ds_read_b128 v[208:211], v148 offset:54272
	ds_read_b128 v[226:229], v148 offset:55296
	ds_read_b128 v[230:233], v148 offset:56320
	global_load_lds_dwordx4 v[142:143], off
	s_add_i32 m0, s14, 0x2000
	s_add_u32 s14, s18, 0x160080
	v_lshl_add_u64 v[142:143], v[166:167], 0, s[58:59]
	s_addc_u32 s15, s19, 0
	s_add_i32 s18, s53, s27
	global_load_lds_dwordx4 v[142:143], off
	v_lshl_add_u64 v[142:143], s[14:15], 0, v[2:3]
	s_mov_b32 m0, s18
	s_nop 0
	global_load_lds_dwordx4 v[142:143], off
	v_lshl_add_u64 v[142:143], s[14:15], 0, v[136:137]
	s_add_i32 m0, s18, 0x2000
	s_nop 0
	global_load_lds_dwordx4 v[142:143], off
	v_lshl_add_u64 v[142:143], v[212:213], 0, s[58:59]
	s_mov_b32 m0, s38
	s_nop 0
	global_load_lds_dwordx4 v[142:143], off
	v_lshl_add_u64 v[142:143], v[234:235], 0, s[58:59]
	s_mov_b32 m0, s39
	s_nop 0
	global_load_lds_dwordx4 v[142:143], off
	s_waitcnt vmcnt(8)
	s_waitcnt lgkmcnt(0)
	s_barrier
	v_mfma_f32_16x16x32_bf16 v[64:67], v[150:153], v[188:191], v[64:67]
	v_mfma_f32_16x16x32_bf16 v[60:63], v[158:161], v[188:191], v[60:63]
	v_mfma_f32_16x16x32_bf16 v[56:59], v[150:153], v[196:199], v[56:59]
	v_mfma_f32_16x16x32_bf16 v[48:51], v[158:161], v[196:199], v[48:51]
	v_mfma_f32_16x16x32_bf16 v[40:43], v[150:153], v[204:207], v[40:43]
	v_mfma_f32_16x16x32_bf16 v[32:35], v[158:161], v[204:207], v[32:35]
	v_mfma_f32_16x16x32_bf16 v[24:27], v[150:153], v[226:229], v[24:27]
	v_mfma_f32_16x16x32_bf16 v[16:19], v[158:161], v[226:229], v[16:19]
	v_mfma_f32_16x16x32_bf16 v[64:67], v[154:157], v[192:195], v[64:67]
	v_mfma_f32_16x16x32_bf16 v[60:63], v[162:165], v[192:195], v[60:63]
	v_mfma_f32_16x16x32_bf16 v[56:59], v[154:157], v[200:203], v[56:59]
	v_mfma_f32_16x16x32_bf16 v[48:51], v[162:165], v[200:203], v[48:51]
	v_mfma_f32_16x16x32_bf16 v[40:43], v[154:157], v[208:211], v[40:43]
	v_mfma_f32_16x16x32_bf16 v[32:35], v[162:165], v[208:211], v[32:35]
	v_mfma_f32_16x16x32_bf16 v[24:27], v[154:157], v[230:233], v[24:27]
	v_mfma_f32_16x16x32_bf16 v[16:19], v[162:165], v[230:233], v[16:19]
	v_mfma_f32_16x16x32_bf16 v[52:55], v[172:175], v[188:191], v[52:55]
	v_mfma_f32_16x16x32_bf16 v[44:47], v[180:183], v[188:191], v[44:47]
	v_mfma_f32_16x16x32_bf16 v[36:39], v[172:175], v[196:199], v[36:39]
	v_mfma_f32_16x16x32_bf16 v[28:31], v[180:183], v[196:199], v[28:31]
	v_mfma_f32_16x16x32_bf16 v[20:23], v[172:175], v[204:207], v[20:23]
	v_mfma_f32_16x16x32_bf16 v[12:15], v[180:183], v[204:207], v[12:15]
	v_mfma_f32_16x16x32_bf16 v[8:11], v[172:175], v[226:229], v[8:11]
	v_mfma_f32_16x16x32_bf16 v[4:7], v[180:183], v[226:229], v[4:7]
	v_mfma_f32_16x16x32_bf16 v[52:55], v[176:179], v[192:195], v[52:55]
	v_mfma_f32_16x16x32_bf16 v[44:47], v[184:187], v[192:195], v[44:47]
	v_mfma_f32_16x16x32_bf16 v[36:39], v[176:179], v[200:203], v[36:39]
	v_mfma_f32_16x16x32_bf16 v[28:31], v[184:187], v[200:203], v[28:31]
	v_mfma_f32_16x16x32_bf16 v[20:23], v[176:179], v[208:211], v[20:23]
	v_mfma_f32_16x16x32_bf16 v[12:15], v[184:187], v[208:211], v[12:15]
	v_mfma_f32_16x16x32_bf16 v[8:11], v[176:179], v[230:233], v[8:11]
	v_mfma_f32_16x16x32_bf16 v[4:7], v[184:187], v[230:233], v[4:7]
	s_barrier
	s_add_u32 s49, s49, 0x100
	s_addc_u32 s50, s50, 0
	s_cmp_ge_i32 s51, s44
	s_mov_b64 s[14:15], s[16:17]
	s_mov_b32 s18, s51
	s_cbranch_scc0 .LBB0_430
	s_branch .Lgemm_after_1

; #define PG8_STAGE(bufoff, gbase, voff) do { _Pragma("unroll") for (int _i = 0; _i < 2; ++_i) \
;         __builtin_amdgcn_global_load_lds((const unsigned*)((const char*)(gbase) + (voff)[_i]), (PG8_LAS unsigned*)(lds + (bufoff) + ldsw + _i * 8192), 16, 0, 0); } while (0)
; #define PG8_LDA(dst, b, h) do { _Pragma("unroll") for (int m = 0; m < 4; ++m) _Pragma("unroll") for (int k = 0; k < 2; ++k) dst[m][k] = *(const PG8_LAS bf16x8*)(lds + PG8_SA(b, h) + aoffk[k] + m * 2048); } while (0)
; #define PG8_WAIT_V(n) asm volatile("s_waitcnt vmcnt(" #n ")" ::: "memory")
; #define PG8_BAR __builtin_amdgcn_s_barrier()
; template <class Epi, class Sched, bool ALIGN_EPI = false, bool SP2 = false>
; __device__ __forceinline__ void gemm_phase(PG8_LAS unsigned char* lds, const Gemm g, const Sched& S, const Epi& E) {
;     ...
;     f32x4 acc[2][2][4][2];
; #pragma unroll
;     for (int a = 0; a < 2; ++a)
; #pragma unroll
;         for (int b = 0; b < 2; ++b)
; #pragma unroll
;             for (int m = 0; m < 4; ++m)
; #pragma unroll
;                 for (int n = 0; n < 2; ++n) acc[a][b][m][n] = (f32x4){0.f, 0.f, 0.f, 0.f};
;     ...
;         const bool has_next = S.next(ui + 1, nxt);
;         const char* nA = has_next ? (const char*)g.A + (size_t)nxt.pm * tstepA + (size_t)nxt.kt0 * kstep : cA; const char* nB = has_next ? (const char*)g.Bt + (size_t)nxt.pn * tstepB + (size_t)nxt.kt0 * kstep : cB;
;         const int nt = cur.nt;
;         for (int t = 0; t < nt; t += 2) {
;             const bool last = (t == nt - 2);
;             const char* a1 = cA + (size_t)(t + 1) * kstep;
;             const char* a2 = last ? nA : cA + (size_t)(t + 2) * kstep; const char* b2 = last ? nB : cB + (size_t)(t + 2) * kstep;
;             const char* a3 = a2 + kstep; const char* b3 = b2 + kstep;
;             if (last && has_next) S.a_ready(nxt);
;             if constexpr (SP2) {
;             PG8_LDB(B0, 0, 0); PG8_LDB(B1, 0, 1); PG8_SCHED; PG8_LDA(At, 0, 0); PG8_STAGE(PG8_SA(1, 1), a1 + hstepA, voffA);
;             PG8_WAIT_V(8); PG8_WAIT_L(0); PG8_BAR; PG8_MMA(0, 0, At, B0); PG8_MMA(0, 1, At, B1); PG8_BAR; PG8_SCHED;
;             PG8_LDA(At, 0, 1); PG8_STAGE(PG8_SB(0, 0), b2, voffB); PG8_STAGE(PG8_SB(0, 1), b2 + hstepB, voffB); PG8_STAGE(PG8_SA(0, 0), a2, voffA);
;             PG8_WAIT_V(8); PG8_WAIT_L(0); PG8_BAR; PG8_MMA(1, 0, At, B0); PG8_MMA(1, 1, At, B1); PG8_BAR; PG8_SCHED;
.LBB0_662:
	s_ashr_i32 s9, s8, 31
	s_lshl_b64 s[14:15], s[8:9], 20
	s_add_u32 s14, s26, s14
	s_addc_u32 s15, s27, s15
	s_and_b64 s[16:17], s[12:13], exec
	s_cselect_b32 s9, s15, s19
	s_cselect_b32 s40, s14, s18
	s_ashr_i32 s7, s6, 31
	s_lshl_b64 s[16:17], s[6:7], 20
	s_add_u32 s16, s28, s16
	s_addc_u32 s17, s29, s17
	s_and_b64 s[22:23], s[12:13], exec
	s_cselect_b32 s7, s17, s21
	s_cselect_b32 s41, s16, s20
	s_add_u32 s18, s18, 0x80080
	s_addc_u32 s19, s19, 0
	s_add_u32 s42, s20, 0x100
	s_addc_u32 s43, s21, 0
	s_mov_b32 s44, -2
	v_readlane_b32 s49, v253, 28
	v_readlane_b32 s50, v253, 29
	v_readlane_b32 s51, v253, 30
	v_readlane_b32 s52, v253, 31
	s_mov_b64 s[56:57], 0x80
.Lgemm_first_2:
	s_add_u32 s20, s18, 0xfff80080
	s_addc_u32 s21, s19, -1
	s_add_i32 s45, 0, 0x10000
	s_cmp_eq_u32 s44, 28
	v_add_u32_e32 v142, s45, v147
	v_add_u32_e32 v151, s45, v148
	s_cselect_b32 s23, s9, s21
	s_cselect_b32 s22, s40, s20
	ds_read_b128 v[142:145], v142
	ds_read_b128 v[152:155], v151
	v_add_u32_e32 v151, s49, v147
	v_add_u32_e32 v160, s49, v148
	s_cselect_b32 s21, s7, s43
	s_cselect_b32 s20, s41, s42
	s_add_i32 s48, 0, 0x14000
	ds_read_b128 v[156:159], v151
	ds_read_b128 v[160:163], v160
	v_add_u32_e32 v151, s48, v147
	v_add_u32_e32 v168, s48, v148
	ds_read_b128 v[164:167], v151
	ds_read_b128 v[172:175], v168
	v_add_u32_e32 v151, s50, v147
	v_add_u32_e32 v168, s50, v148
	ds_read_b128 v[176:179], v151
	ds_read_b128 v[180:183], v168
	v_lshl_add_u64 v[212:213], s[18:19], 0, v[138:139]
	s_add_i32 m0, s33, 0xc000
	ds_read_b128 v[184:187], v150
	ds_read_b128 v[188:191], v150 offset:1024
	ds_read_b128 v[192:195], v150 offset:2048
	ds_read_b128 v[196:199], v150 offset:3072
	ds_read_b128 v[200:203], v150 offset:4096
	ds_read_b128 v[204:207], v150 offset:5120
	ds_read_b128 v[208:211], v150 offset:6144
	ds_read_b128 v[226:229], v150 offset:7168
	global_load_lds_dwordx4 v[212:213], off
	v_lshl_add_u64 v[212:213], s[18:19], 0, v[140:141]
	s_add_i32 m0, s33, 0xe000
	s_nop 0
	global_load_lds_dwordx4 v[212:213], off
	s_waitcnt vmcnt(8)
	s_waitcnt lgkmcnt(0)
	s_barrier
	v_mfma_f32_16x16x32_bf16 v[128:131], v[142:145], v[184:187], 0
	v_mfma_f32_16x16x32_bf16 v[124:127], v[156:159], v[184:187], 0
	v_mfma_f32_16x16x32_bf16 v[120:123], v[142:145], v[192:195], 0
	v_mfma_f32_16x16x32_bf16 v[112:115], v[156:159], v[192:195], 0
	v_mfma_f32_16x16x32_bf16 v[104:107], v[142:145], v[200:203], 0
	v_mfma_f32_16x16x32_bf16 v[96:99], v[156:159], v[200:203], 0
	v_mfma_f32_16x16x32_bf16 v[88:91], v[142:145], v[208:211], 0
	v_mfma_f32_16x16x32_bf16 v[80:83], v[156:159], v[208:211], 0
	v_mfma_f32_16x16x32_bf16 v[128:131], v[152:155], v[188:191], v[128:131]
	v_mfma_f32_16x16x32_bf16 v[124:127], v[160:163], v[188:191], v[124:127]
	v_mfma_f32_16x16x32_bf16 v[120:123], v[152:155], v[196:199], v[120:123]
	v_mfma_f32_16x16x32_bf16 v[112:115], v[160:163], v[196:199], v[112:115]
	v_mfma_f32_16x16x32_bf16 v[104:107], v[152:155], v[204:207], v[104:107]
	v_mfma_f32_16x16x32_bf16 v[96:99], v[160:163], v[204:207], v[96:99]
	v_mfma_f32_16x16x32_bf16 v[88:91], v[152:155], v[226:229], v[88:91]
	v_mfma_f32_16x16x32_bf16 v[80:83], v[160:163], v[226:229], v[80:83]
	v_mfma_f32_16x16x32_bf16 v[116:119], v[164:167], v[184:187], 0
	v_mfma_f32_16x16x32_bf16 v[108:111], v[176:179], v[184:187], 0
	v_mfma_f32_16x16x32_bf16 v[100:103], v[164:167], v[192:195], 0
	v_mfma_f32_16x16x32_bf16 v[92:95], v[176:179], v[192:195], 0
	v_mfma_f32_16x16x32_bf16 v[84:87], v[164:167], v[200:203], 0
	v_mfma_f32_16x16x32_bf16 v[76:79], v[176:179], v[200:203], 0
	v_mfma_f32_16x16x32_bf16 v[72:75], v[164:167], v[208:211], 0
	v_mfma_f32_16x16x32_bf16 v[68:71], v[176:179], v[208:211], 0
	v_mfma_f32_16x16x32_bf16 v[116:119], v[172:175], v[188:191], v[116:119]
	v_mfma_f32_16x16x32_bf16 v[108:111], v[180:183], v[188:191], v[108:111]
	v_mfma_f32_16x16x32_bf16 v[100:103], v[172:175], v[196:199], v[100:103]
	v_mfma_f32_16x16x32_bf16 v[92:95], v[180:183], v[196:199], v[92:95]
	v_mfma_f32_16x16x32_bf16 v[84:87], v[172:175], v[204:207], v[84:87]
	v_mfma_f32_16x16x32_bf16 v[76:79], v[180:183], v[204:207], v[76:79]
	v_mfma_f32_16x16x32_bf16 v[72:75], v[172:175], v[226:229], v[72:75]
	v_mfma_f32_16x16x32_bf16 v[68:71], v[180:183], v[226:229], v[68:71]
	s_barrier
	s_add_i32 s45, s45, s30
	v_lshl_add_u64 v[212:213], s[20:21], 0, v[2:3]
	s_mov_b32 m0, s45
	ds_read_b128 v[184:187], v150 offset:16384
	ds_read_b128 v[188:191], v150 offset:17408
	ds_read_b128 v[192:195], v150 offset:18432
	ds_read_b128 v[196:199], v150 offset:19456
	ds_read_b128 v[200:203], v150 offset:20480
	ds_read_b128 v[204:207], v150 offset:21504
	ds_read_b128 v[208:211], v150 offset:22528
	ds_read_b128 v[226:229], v150 offset:23552
	global_load_lds_dwordx4 v[212:213], off
	s_add_i32 m0, s45, 0x2000
	s_add_u32 s46, s20, 0x80000
	v_lshl_add_u64 v[230:231], s[20:21], 0, v[132:133]
	s_addc_u32 s47, s21, 0
	s_add_i32 s45, s48, s30
	global_load_lds_dwordx4 v[230:231], off
	v_lshl_add_u64 v[232:233], s[46:47], 0, v[2:3]
	s_mov_b32 m0, s45
	v_lshl_add_u64 v[234:235], s[22:23], 0, v[134:135]
	global_load_lds_dwordx4 v[232:233], off
	v_lshl_add_u64 v[232:233], s[46:47], 0, v[132:133]
	s_add_i32 m0, s45, 0x2000
	s_nop 0
	global_load_lds_dwordx4 v[232:233], off
	v_lshl_add_u64 v[232:233], s[22:23], 0, v[136:137]
	s_mov_b32 m0, s33
	s_nop 0
	global_load_lds_dwordx4 v[232:233], off
	s_mov_b32 m0, s34
	s_nop 0
	global_load_lds_dwordx4 v[234:235], off
	s_waitcnt vmcnt(8)
	s_waitcnt lgkmcnt(0)
	s_barrier
; #define PG8_STAGE(bufoff, gbase, voff) do { _Pragma("unroll") for (int _i = 0; _i < 2; ++_i) \
;         __builtin_amdgcn_global_load_lds((const unsigned*)((const char*)(gbase) + (voff)[_i]), (PG8_LAS unsigned*)(lds + (bufoff) + ldsw + _i * 8192), 16, 0, 0); } while (0)
; #define PG8_LDA(dst, b, h) do { _Pragma("unroll") for (int m = 0; m < 4; ++m) _Pragma("unroll") for (int k = 0; k < 2; ++k) dst[m][k] = *(const PG8_LAS bf16x8*)(lds + PG8_SA(b, h) + aoffk[k] + m * 2048); } while (0)
; #define PG8_LDB(dst, b, h) do { _Pragma("unroll") for (int n = 0; n < 2; ++n) _Pragma("unroll") for (int k = 0; k < 2; ++k) dst[n][k] = *(const PG8_LAS bf16x8*)(lds + PG8_SB(b, h) + boffk[k] + n * 2048); } while (0)
; #define PG8_MMA(ai, bj, At, Bt) do { __builtin_amdgcn_s_setprio(1); _Pragma("unroll") for (int m = 0; m < 4; ++m) _Pragma("unroll") for (int n = 0; n < 2; ++n) _Pragma("unroll") for (int k = 0; k < 2; ++k) \
;         acc[ai][bj][m][n] = __builtin_amdgcn_mfma_f32_16x16x32_bf16(Bt[n][k], At[m][k], acc[ai][bj][m][n], 0, 0, 0); __builtin_amdgcn_s_setprio(0); } while (0)
; #define PG8_WAIT_V(n) asm volatile("s_waitcnt vmcnt(" #n ")" ::: "memory")
; #define PG8_WAIT_L(n) asm volatile("s_waitcnt lgkmcnt(" #n ")" ::: "memory")
; #define PG8_BAR __builtin_amdgcn_s_barrier()
; #define PG8_SCHED __builtin_amdgcn_sched_barrier(0)
; template <class Epi, class Sched, bool ALIGN_EPI = false, bool SP2 = false>
; __device__ __forceinline__ void gemm_phase(PG8_LAS unsigned char* lds, const Gemm g, const Sched& S, const Epi& E) {
;     ...
;             PG8_LDA(At, 0, 1); PG8_STAGE(PG8_SB(0, 0), b2, voffB); PG8_STAGE(PG8_SB(0, 1), b2 + hstepB, voffB); PG8_STAGE(PG8_SA(0, 0), a2, voffA);
;             PG8_WAIT_V(8); PG8_WAIT_L(0); PG8_BAR; PG8_MMA(1, 0, At, B0); PG8_MMA(1, 1, At, B1); PG8_BAR; PG8_SCHED;
;             PG8_LDB(B0, 1, 0); PG8_LDB(B1, 1, 1); PG8_SCHED; PG8_LDA(At, 1, 0); PG8_STAGE(PG8_SA(0, 1), a2 + hstepA, voffA);
;             PG8_WAIT_V(8); PG8_WAIT_L(0); PG8_BAR; PG8_MMA(0, 0, At, B0); PG8_MMA(0, 1, At, B1); PG8_BAR; PG8_SCHED;
	v_mfma_f32_16x16x32_bf16 v[64:67], v[142:145], v[184:187], 0
	v_mfma_f32_16x16x32_bf16 v[60:63], v[156:159], v[184:187], 0
	v_mfma_f32_16x16x32_bf16 v[56:59], v[142:145], v[192:195], 0
	v_mfma_f32_16x16x32_bf16 v[48:51], v[156:159], v[192:195], 0
	v_mfma_f32_16x16x32_bf16 v[40:43], v[142:145], v[200:203], 0
	v_mfma_f32_16x16x32_bf16 v[32:35], v[156:159], v[200:203], 0
	v_mfma_f32_16x16x32_bf16 v[24:27], v[142:145], v[208:211], 0
	v_mfma_f32_16x16x32_bf16 v[16:19], v[156:159], v[208:211], 0
	v_mfma_f32_16x16x32_bf16 v[64:67], v[152:155], v[188:191], v[64:67]
	v_mfma_f32_16x16x32_bf16 v[60:63], v[160:163], v[188:191], v[60:63]
	v_mfma_f32_16x16x32_bf16 v[56:59], v[152:155], v[196:199], v[56:59]
	v_mfma_f32_16x16x32_bf16 v[48:51], v[160:163], v[196:199], v[48:51]
	v_mfma_f32_16x16x32_bf16 v[40:43], v[152:155], v[204:207], v[40:43]
	v_mfma_f32_16x16x32_bf16 v[32:35], v[160:163], v[204:207], v[32:35]
	v_mfma_f32_16x16x32_bf16 v[24:27], v[152:155], v[226:229], v[24:27]
	v_mfma_f32_16x16x32_bf16 v[16:19], v[160:163], v[226:229], v[16:19]
	v_mfma_f32_16x16x32_bf16 v[52:55], v[164:167], v[184:187], 0
	v_mfma_f32_16x16x32_bf16 v[44:47], v[176:179], v[184:187], 0
	v_mfma_f32_16x16x32_bf16 v[36:39], v[164:167], v[192:195], 0
	v_mfma_f32_16x16x32_bf16 v[28:31], v[176:179], v[192:195], 0
	v_mfma_f32_16x16x32_bf16 v[20:23], v[164:167], v[200:203], 0
	v_mfma_f32_16x16x32_bf16 v[12:15], v[176:179], v[200:203], 0
	v_mfma_f32_16x16x32_bf16 v[8:11], v[164:167], v[208:211], 0
	v_mfma_f32_16x16x32_bf16 v[4:7], v[176:179], v[208:211], 0
	v_mfma_f32_16x16x32_bf16 v[52:55], v[172:175], v[188:191], v[52:55]
	v_mfma_f32_16x16x32_bf16 v[44:47], v[180:183], v[188:191], v[44:47]
	v_mfma_f32_16x16x32_bf16 v[36:39], v[172:175], v[196:199], v[36:39]
	v_mfma_f32_16x16x32_bf16 v[28:31], v[180:183], v[196:199], v[28:31]
	v_mfma_f32_16x16x32_bf16 v[20:23], v[172:175], v[204:207], v[20:23]
	v_mfma_f32_16x16x32_bf16 v[12:15], v[180:183], v[204:207], v[12:15]
	v_mfma_f32_16x16x32_bf16 v[8:11], v[172:175], v[226:229], v[8:11]
	v_mfma_f32_16x16x32_bf16 v[4:7], v[180:183], v[226:229], v[4:7]
	s_barrier
	s_add_i32 s45, 0, 0x18000
	v_add_u32_e32 v142, s45, v147
	v_add_u32_e32 v151, s45, v148
	ds_read_b128 v[142:145], v142
	ds_read_b128 v[152:155], v151
	v_add_u32_e32 v151, s51, v147
	v_add_u32_e32 v160, s51, v148
	s_add_i32 s46, 0, 0x1c000
	ds_read_b128 v[156:159], v151
	ds_read_b128 v[160:163], v160
	v_add_u32_e32 v151, s46, v147
	v_add_u32_e32 v168, s46, v148
	ds_read_b128 v[164:167], v151
	ds_read_b128 v[172:175], v168
	v_add_u32_e32 v151, s52, v147
	v_add_u32_e32 v168, s52, v148
	ds_read_b128 v[176:179], v151
	ds_read_b128 v[180:183], v168
	s_add_u32 s22, s22, 0x80000
	s_addc_u32 s23, s23, 0
	s_mov_b32 m0, s35
	v_lshl_add_u64 v[236:237], s[22:23], 0, v[136:137]
	ds_read_b128 v[184:187], v150 offset:32768
	ds_read_b128 v[188:191], v150 offset:33792
	ds_read_b128 v[192:195], v150 offset:34816
	ds_read_b128 v[196:199], v150 offset:35840
	ds_read_b128 v[200:203], v150 offset:36864
	ds_read_b128 v[204:207], v150 offset:37888
	ds_read_b128 v[208:211], v150 offset:38912
	ds_read_b128 v[226:229], v150 offset:39936
	global_load_lds_dwordx4 v[236:237], off
	v_lshl_add_u64 v[236:237], s[22:23], 0, v[134:135]
	s_mov_b32 m0, s36
	s_nop 0
	global_load_lds_dwordx4 v[236:237], off
	s_waitcnt vmcnt(8)
	s_waitcnt lgkmcnt(0)
	s_barrier
	v_mfma_f32_16x16x32_bf16 v[128:131], v[142:145], v[184:187], v[128:131]
	v_mfma_f32_16x16x32_bf16 v[124:127], v[156:159], v[184:187], v[124:127]
	v_mfma_f32_16x16x32_bf16 v[120:123], v[142:145], v[192:195], v[120:123]
	v_mfma_f32_16x16x32_bf16 v[112:115], v[156:159], v[192:195], v[112:115]
	v_mfma_f32_16x16x32_bf16 v[104:107], v[142:145], v[200:203], v[104:107]
	v_mfma_f32_16x16x32_bf16 v[96:99], v[156:159], v[200:203], v[96:99]
	v_mfma_f32_16x16x32_bf16 v[88:91], v[142:145], v[208:211], v[88:91]
	v_mfma_f32_16x16x32_bf16 v[80:83], v[156:159], v[208:211], v[80:83]
	v_mfma_f32_16x16x32_bf16 v[128:131], v[152:155], v[188:191], v[128:131]
	v_mfma_f32_16x16x32_bf16 v[124:127], v[160:163], v[188:191], v[124:127]
	v_mfma_f32_16x16x32_bf16 v[120:123], v[152:155], v[196:199], v[120:123]
	v_mfma_f32_16x16x32_bf16 v[112:115], v[160:163], v[196:199], v[112:115]
	v_mfma_f32_16x16x32_bf16 v[104:107], v[152:155], v[204:207], v[104:107]
	v_mfma_f32_16x16x32_bf16 v[96:99], v[160:163], v[204:207], v[96:99]
	v_mfma_f32_16x16x32_bf16 v[88:91], v[152:155], v[226:229], v[88:91]
	v_mfma_f32_16x16x32_bf16 v[80:83], v[160:163], v[226:229], v[80:83]
	v_mfma_f32_16x16x32_bf16 v[116:119], v[164:167], v[184:187], v[116:119]
	v_mfma_f32_16x16x32_bf16 v[108:111], v[176:179], v[184:187], v[108:111]
	v_mfma_f32_16x16x32_bf16 v[100:103], v[164:167], v[192:195], v[100:103]
	v_mfma_f32_16x16x32_bf16 v[92:95], v[176:179], v[192:195], v[92:95]
	v_mfma_f32_16x16x32_bf16 v[84:87], v[164:167], v[200:203], v[84:87]
	v_mfma_f32_16x16x32_bf16 v[76:79], v[176:179], v[200:203], v[76:79]
	v_mfma_f32_16x16x32_bf16 v[72:75], v[164:167], v[208:211], v[72:75]
	v_mfma_f32_16x16x32_bf16 v[68:71], v[176:179], v[208:211], v[68:71]
	v_mfma_f32_16x16x32_bf16 v[116:119], v[172:175], v[188:191], v[116:119]
	v_mfma_f32_16x16x32_bf16 v[108:111], v[180:183], v[188:191], v[108:111]
	v_mfma_f32_16x16x32_bf16 v[100:103], v[172:175], v[196:199], v[100:103]
	v_mfma_f32_16x16x32_bf16 v[92:95], v[180:183], v[196:199], v[92:95]
	v_mfma_f32_16x16x32_bf16 v[84:87], v[172:175], v[204:207], v[84:87]
	v_mfma_f32_16x16x32_bf16 v[76:79], v[180:183], v[204:207], v[76:79]
	v_mfma_f32_16x16x32_bf16 v[72:75], v[172:175], v[226:229], v[72:75]
	v_mfma_f32_16x16x32_bf16 v[68:71], v[180:183], v[226:229], v[68:71]
	s_barrier
; #define PG8_STAGE(bufoff, gbase, voff) do { _Pragma("unroll") for (int _i = 0; _i < 2; ++_i) \
;         __builtin_amdgcn_global_load_lds((const unsigned*)((const char*)(gbase) + (voff)[_i]), (PG8_LAS unsigned*)(lds + (bufoff) + ldsw + _i * 8192), 16, 0, 0); } while (0)
; #define PG8_LDA(dst, b, h) do { _Pragma("unroll") for (int m = 0; m < 4; ++m) _Pragma("unroll") for (int k = 0; k < 2; ++k) dst[m][k] = *(const PG8_LAS bf16x8*)(lds + PG8_SA(b, h) + aoffk[k] + m * 2048); } while (0)
; #define PG8_MMA(ai, bj, At, Bt) do { __builtin_amdgcn_s_setprio(1); _Pragma("unroll") for (int m = 0; m < 4; ++m) _Pragma("unroll") for (int n = 0; n < 2; ++n) _Pragma("unroll") for (int k = 0; k < 2; ++k) \
;         acc[ai][bj][m][n] = __builtin_amdgcn_mfma_f32_16x16x32_bf16(Bt[n][k], At[m][k], acc[ai][bj][m][n], 0, 0, 0); __builtin_amdgcn_s_setprio(0); } while (0)
; #define PG8_WAIT_V(n) asm volatile("s_waitcnt vmcnt(" #n ")" ::: "memory")
; #define PG8_WAIT_L(n) asm volatile("s_waitcnt lgkmcnt(" #n ")" ::: "memory")
; #define PG8_BAR __builtin_amdgcn_s_barrier()
; #define PG8_SCHED __builtin_amdgcn_sched_barrier(0)
; template <class Epi, class Sched, bool ALIGN_EPI = false, bool SP2 = false>
; __device__ __forceinline__ void gemm_phase(PG8_LAS unsigned char* lds, const Gemm g, const Sched& S, const Epi& E) {
;     ...
;         for (int t = 0; t < nt; t += 2) {
;             const bool last = (t == nt - 2);
;             const char* a1 = cA + (size_t)(t + 1) * kstep;
;             const char* a2 = last ? nA : cA + (size_t)(t + 2) * kstep; const char* b2 = last ? nB : cB + (size_t)(t + 2) * kstep;
;             const char* a3 = a2 + kstep; const char* b3 = b2 + kstep;
;     ...
;             PG8_LDA(At, 1, 1); PG8_STAGE(PG8_SB(1, 0), b3, voffB); PG8_STAGE(PG8_SB(1, 1), b3 + hstepB, voffB); PG8_STAGE(PG8_SA(1, 0), a3, voffA);
;             PG8_WAIT_V(8); PG8_WAIT_L(0); PG8_BAR; PG8_MMA(1, 0, At, B0); PG8_MMA(1, 1, At, B1); PG8_BAR; PG8_SCHED;
	s_add_i32 s22, s45, s30
	v_lshl_add_u64 v[212:213], v[212:213], 0, s[56:57]
	s_mov_b32 m0, s22
	ds_read_b128 v[184:187], v150 offset:49152
	ds_read_b128 v[188:191], v150 offset:50176
	ds_read_b128 v[192:195], v150 offset:51200
	ds_read_b128 v[196:199], v150 offset:52224
	ds_read_b128 v[200:203], v150 offset:53248
	ds_read_b128 v[204:207], v150 offset:54272
	ds_read_b128 v[208:211], v150 offset:55296
	ds_read_b128 v[226:229], v150 offset:56320
	global_load_lds_dwordx4 v[212:213], off
	s_add_i32 m0, s22, 0x2000
	s_add_u32 s20, s20, 0x80080
	v_lshl_add_u64 v[212:213], v[230:231], 0, s[56:57]
	s_addc_u32 s21, s21, 0
	s_add_i32 s22, s46, s30
	global_load_lds_dwordx4 v[212:213], off
	v_lshl_add_u64 v[212:213], s[20:21], 0, v[2:3]
	s_mov_b32 m0, s22
	s_nop 0
	global_load_lds_dwordx4 v[212:213], off
	v_lshl_add_u64 v[212:213], s[20:21], 0, v[132:133]
	s_add_i32 m0, s22, 0x2000
	s_nop 0
	global_load_lds_dwordx4 v[212:213], off
	v_lshl_add_u64 v[212:213], v[232:233], 0, s[56:57]
	s_mov_b32 m0, s37
	s_nop 0
	global_load_lds_dwordx4 v[212:213], off
	v_lshl_add_u64 v[212:213], v[234:235], 0, s[56:57]
	s_mov_b32 m0, s38
	s_nop 0
	global_load_lds_dwordx4 v[212:213], off
	s_waitcnt vmcnt(8)
	s_waitcnt lgkmcnt(0)
	s_barrier
	v_mfma_f32_16x16x32_bf16 v[64:67], v[142:145], v[184:187], v[64:67]
	v_mfma_f32_16x16x32_bf16 v[60:63], v[156:159], v[184:187], v[60:63]
	v_mfma_f32_16x16x32_bf16 v[56:59], v[142:145], v[192:195], v[56:59]
	v_mfma_f32_16x16x32_bf16 v[48:51], v[156:159], v[192:195], v[48:51]
	v_mfma_f32_16x16x32_bf16 v[40:43], v[142:145], v[200:203], v[40:43]
	v_mfma_f32_16x16x32_bf16 v[32:35], v[156:159], v[200:203], v[32:35]
	v_mfma_f32_16x16x32_bf16 v[24:27], v[142:145], v[208:211], v[24:27]
	v_mfma_f32_16x16x32_bf16 v[16:19], v[156:159], v[208:211], v[16:19]
	v_mfma_f32_16x16x32_bf16 v[64:67], v[152:155], v[188:191], v[64:67]
	v_mfma_f32_16x16x32_bf16 v[60:63], v[160:163], v[188:191], v[60:63]
	v_mfma_f32_16x16x32_bf16 v[56:59], v[152:155], v[196:199], v[56:59]
	v_mfma_f32_16x16x32_bf16 v[48:51], v[160:163], v[196:199], v[48:51]
	v_mfma_f32_16x16x32_bf16 v[40:43], v[152:155], v[204:207], v[40:43]
	v_mfma_f32_16x16x32_bf16 v[32:35], v[160:163], v[204:207], v[32:35]
	v_mfma_f32_16x16x32_bf16 v[24:27], v[152:155], v[226:229], v[24:27]
	v_mfma_f32_16x16x32_bf16 v[16:19], v[160:163], v[226:229], v[16:19]
	v_mfma_f32_16x16x32_bf16 v[52:55], v[164:167], v[184:187], v[52:55]
	v_mfma_f32_16x16x32_bf16 v[44:47], v[176:179], v[184:187], v[44:47]
	v_mfma_f32_16x16x32_bf16 v[36:39], v[164:167], v[192:195], v[36:39]
	v_mfma_f32_16x16x32_bf16 v[28:31], v[176:179], v[192:195], v[28:31]
	v_mfma_f32_16x16x32_bf16 v[20:23], v[164:167], v[200:203], v[20:23]
	v_mfma_f32_16x16x32_bf16 v[12:15], v[176:179], v[200:203], v[12:15]
	v_mfma_f32_16x16x32_bf16 v[8:11], v[164:167], v[208:211], v[8:11]
	v_mfma_f32_16x16x32_bf16 v[4:7], v[176:179], v[208:211], v[4:7]
	v_mfma_f32_16x16x32_bf16 v[52:55], v[172:175], v[188:191], v[52:55]
	v_mfma_f32_16x16x32_bf16 v[44:47], v[180:183], v[188:191], v[44:47]
	v_mfma_f32_16x16x32_bf16 v[36:39], v[172:175], v[196:199], v[36:39]
	v_mfma_f32_16x16x32_bf16 v[28:31], v[180:183], v[196:199], v[28:31]
	v_mfma_f32_16x16x32_bf16 v[20:23], v[172:175], v[204:207], v[20:23]
	v_mfma_f32_16x16x32_bf16 v[12:15], v[180:183], v[204:207], v[12:15]
	v_mfma_f32_16x16x32_bf16 v[8:11], v[172:175], v[226:229], v[8:11]
	v_mfma_f32_16x16x32_bf16 v[4:7], v[180:183], v[226:229], v[4:7]
	s_barrier
	s_add_i32 s44, s44, 2
	s_add_u32 s18, s18, 0x100
	s_addc_u32 s19, s19, 0
	s_add_u32 s42, s42, 0x100
	s_addc_u32 s43, s43, 0
	s_cmp_gt_u32 s44, 29
	s_cbranch_scc0 .LBB0_663
	s_branch .Lgemm_after_2

; #define PG8_BAR __builtin_amdgcn_s_barrier()
; template <class Epi, class Sched, bool ALIGN_EPI = false, bool SP2 = false>
; __device__ __forceinline__ void gemm_phase(PG8_LAS unsigned char* lds, const Gemm g, const Sched& S, const Epi& E) {
;     ...
;         if constexpr (ALIGN_EPI) { if (wr == 0) PG8_BAR; }
.Lgemm_after_2:
	s_and_b64 vcc, exec, s[4:5]
	s_cbranch_vccz .LBB0_666
	s_barrier

; #define PG8_STAGE(bufoff, gbase, voff) do { _Pragma("unroll") for (int _i = 0; _i < 2; ++_i) \
;         __builtin_amdgcn_global_load_lds((const unsigned*)((const char*)(gbase) + (voff)[_i]), (PG8_LAS unsigned*)(lds + (bufoff) + ldsw + _i * 8192), 16, 0, 0); } while (0)
; #define PG8_LDA(dst, b, h) do { _Pragma("unroll") for (int m = 0; m < 4; ++m) _Pragma("unroll") for (int k = 0; k < 2; ++k) dst[m][k] = *(const PG8_LAS bf16x8*)(lds + PG8_SA(b, h) + aoffk[k] + m * 2048); } while (0)
; #define PG8_WAIT_V(n) asm volatile("s_waitcnt vmcnt(" #n ")" ::: "memory")
; #define PG8_BAR __builtin_amdgcn_s_barrier()
; template <class Epi, class Sched, bool ALIGN_EPI = false, bool SP2 = false>
; __device__ __forceinline__ void gemm_phase(PG8_LAS unsigned char* lds, const Gemm g, const Sched& S, const Epi& E) {
;     ...
;     f32x4 acc[2][2][4][2];
; #pragma unroll
;     for (int a = 0; a < 2; ++a)
; #pragma unroll
;         for (int b = 0; b < 2; ++b)
; #pragma unroll
;             for (int m = 0; m < 4; ++m)
; #pragma unroll
;                 for (int n = 0; n < 2; ++n) acc[a][b][m][n] = (f32x4){0.f, 0.f, 0.f, 0.f};
;     ...
;         const bool has_next = S.next(ui + 1, nxt);
;         const char* nA = has_next ? (const char*)g.A + (size_t)nxt.pm * tstepA + (size_t)nxt.kt0 * kstep : cA; const char* nB = has_next ? (const char*)g.Bt + (size_t)nxt.pn * tstepB + (size_t)nxt.kt0 * kstep : cB;
;         const int nt = cur.nt;
;         for (int t = 0; t < nt; t += 2) {
;             const bool last = (t == nt - 2);
;             const char* a1 = cA + (size_t)(t + 1) * kstep;
;             const char* a2 = last ? nA : cA + (size_t)(t + 2) * kstep; const char* b2 = last ? nB : cB + (size_t)(t + 2) * kstep;
;             const char* a3 = a2 + kstep; const char* b3 = b2 + kstep;
;             if (last && has_next) S.a_ready(nxt);
;             if constexpr (SP2) {
;             PG8_LDB(B0, 0, 0); PG8_LDB(B1, 0, 1); PG8_SCHED; PG8_LDA(At, 0, 0); PG8_STAGE(PG8_SA(1, 1), a1 + hstepA, voffA);
;             PG8_WAIT_V(8); PG8_WAIT_L(0); PG8_BAR; PG8_MMA(0, 0, At, B0); PG8_MMA(0, 1, At, B1); PG8_BAR; PG8_SCHED;
;             PG8_LDA(At, 0, 1); PG8_STAGE(PG8_SB(0, 0), b2, voffB); PG8_STAGE(PG8_SB(0, 1), b2 + hstepB, voffB); PG8_STAGE(PG8_SA(0, 0), a2, voffA);
;             PG8_WAIT_V(8); PG8_WAIT_L(0); PG8_BAR; PG8_MMA(1, 0, At, B0); PG8_MMA(1, 1, At, B1); PG8_BAR; PG8_SCHED;
.LBB0_1292:
	s_add_i32 s11, s45, -2
	s_add_u32 s20, s20, 0x80080
	s_addc_u32 s21, s21, 0
	s_add_u32 s13, s22, 0x100
	s_addc_u32 s15, s23, 0
	s_mov_b32 s22, 0
	v_readlane_b32 s53, v253, 28
	v_readlane_b32 s54, v253, 29
	v_readlane_b32 s55, v253, 30
	v_readlane_b32 s56, v253, 31
	s_mov_b64 s[58:59], 0x80
.Lgemm_first_3:
	s_add_i32 s48, s22, 2
	s_add_u32 s23, s20, 0xfff80080
	s_addc_u32 s24, s21, -1
	s_add_i32 s49, 0, 0x10000
	s_cmp_eq_u32 s11, s22
	v_add_u32_e32 v142, s49, v145
	s_cselect_b32 s25, s17, s24
	s_cselect_b32 s24, s16, s23
	v_add_u32_e32 v143, s49, v146
	ds_read_b128 v[150:153], v142
	ds_read_b128 v[154:157], v143
	v_add_u32_e32 v142, s53, v145
	s_cselect_b32 s23, s19, s15
	s_cselect_b32 s22, s18, s13
	s_add_i32 s52, 0, 0x14000
	v_add_u32_e32 v143, s53, v146
	ds_read_b128 v[158:161], v142
	ds_read_b128 v[162:165], v143
	v_add_u32_e32 v142, s52, v145
	v_add_u32_e32 v143, s52, v146
	ds_read_b128 v[172:175], v142
	ds_read_b128 v[176:179], v143
	v_add_u32_e32 v142, s54, v145
	v_add_u32_e32 v143, s54, v146
	ds_read_b128 v[180:183], v142
	ds_read_b128 v[184:187], v143
	v_lshl_add_u64 v[142:143], s[20:21], 0, v[138:139]
	s_add_i32 m0, s5, 0xc000
	ds_read_b128 v[188:191], v148
	ds_read_b128 v[192:195], v148 offset:1024
	ds_read_b128 v[196:199], v148 offset:2048
	ds_read_b128 v[200:203], v148 offset:3072
	ds_read_b128 v[204:207], v148 offset:4096
	ds_read_b128 v[208:211], v148 offset:5120
	ds_read_b128 v[226:229], v148 offset:6144
	ds_read_b128 v[230:233], v148 offset:7168
	global_load_lds_dwordx4 v[142:143], off
	v_lshl_add_u64 v[142:143], s[20:21], 0, v[140:141]
	s_add_i32 m0, s5, 0xe000
	s_nop 0
	global_load_lds_dwordx4 v[142:143], off
	s_waitcnt vmcnt(8)
	s_waitcnt lgkmcnt(0)
	s_barrier
	v_mfma_f32_16x16x32_bf16 v[128:131], v[150:153], v[188:191], 0
	v_mfma_f32_16x16x32_bf16 v[124:127], v[158:161], v[188:191], 0
	v_mfma_f32_16x16x32_bf16 v[120:123], v[150:153], v[196:199], 0
	v_mfma_f32_16x16x32_bf16 v[112:115], v[158:161], v[196:199], 0
	v_mfma_f32_16x16x32_bf16 v[104:107], v[150:153], v[204:207], 0
	v_mfma_f32_16x16x32_bf16 v[96:99], v[158:161], v[204:207], 0
	v_mfma_f32_16x16x32_bf16 v[88:91], v[150:153], v[226:229], 0
	v_mfma_f32_16x16x32_bf16 v[80:83], v[158:161], v[226:229], 0
	v_mfma_f32_16x16x32_bf16 v[128:131], v[154:157], v[192:195], v[128:131]
	v_mfma_f32_16x16x32_bf16 v[124:127], v[162:165], v[192:195], v[124:127]
	v_mfma_f32_16x16x32_bf16 v[120:123], v[154:157], v[200:203], v[120:123]
	v_mfma_f32_16x16x32_bf16 v[112:115], v[162:165], v[200:203], v[112:115]
	v_mfma_f32_16x16x32_bf16 v[104:107], v[154:157], v[208:211], v[104:107]
	v_mfma_f32_16x16x32_bf16 v[96:99], v[162:165], v[208:211], v[96:99]
	v_mfma_f32_16x16x32_bf16 v[88:91], v[154:157], v[230:233], v[88:91]
	v_mfma_f32_16x16x32_bf16 v[80:83], v[162:165], v[230:233], v[80:83]
	v_mfma_f32_16x16x32_bf16 v[116:119], v[172:175], v[188:191], 0
	v_mfma_f32_16x16x32_bf16 v[108:111], v[180:183], v[188:191], 0
	v_mfma_f32_16x16x32_bf16 v[100:103], v[172:175], v[196:199], 0
	v_mfma_f32_16x16x32_bf16 v[92:95], v[180:183], v[196:199], 0
	v_mfma_f32_16x16x32_bf16 v[84:87], v[172:175], v[204:207], 0
	v_mfma_f32_16x16x32_bf16 v[76:79], v[180:183], v[204:207], 0
	v_mfma_f32_16x16x32_bf16 v[72:75], v[172:175], v[226:229], 0
	v_mfma_f32_16x16x32_bf16 v[68:71], v[180:183], v[226:229], 0
	v_mfma_f32_16x16x32_bf16 v[116:119], v[176:179], v[192:195], v[116:119]
	v_mfma_f32_16x16x32_bf16 v[108:111], v[184:187], v[192:195], v[108:111]
	v_mfma_f32_16x16x32_bf16 v[100:103], v[176:179], v[200:203], v[100:103]
	v_mfma_f32_16x16x32_bf16 v[92:95], v[184:187], v[200:203], v[92:95]
	v_mfma_f32_16x16x32_bf16 v[84:87], v[176:179], v[208:211], v[84:87]
	v_mfma_f32_16x16x32_bf16 v[76:79], v[184:187], v[208:211], v[76:79]
	v_mfma_f32_16x16x32_bf16 v[72:75], v[176:179], v[230:233], v[72:75]
	v_mfma_f32_16x16x32_bf16 v[68:71], v[184:187], v[230:233], v[68:71]
	s_barrier
	s_add_i32 s49, s49, s33
	v_lshl_add_u64 v[142:143], s[22:23], 0, v[2:3]
	s_mov_b32 m0, s49
	ds_read_b128 v[188:191], v148 offset:16384
	ds_read_b128 v[192:195], v148 offset:17408
	ds_read_b128 v[196:199], v148 offset:18432
	ds_read_b128 v[200:203], v148 offset:19456
	ds_read_b128 v[204:207], v148 offset:20480
	ds_read_b128 v[208:211], v148 offset:21504
	ds_read_b128 v[226:229], v148 offset:22528
	ds_read_b128 v[230:233], v148 offset:23552
	global_load_lds_dwordx4 v[142:143], off
	s_add_i32 m0, s49, 0x2000
	s_add_u32 s50, s22, 0x80000
	v_lshl_add_u64 v[166:167], s[22:23], 0, v[136:137]
	s_addc_u32 s51, s23, 0
	s_add_i32 s49, s52, s33
	global_load_lds_dwordx4 v[166:167], off
	v_lshl_add_u64 v[212:213], s[50:51], 0, v[2:3]
	s_mov_b32 m0, s49
	v_lshl_add_u64 v[220:221], s[24:25], 0, v[134:135]
	global_load_lds_dwordx4 v[212:213], off
	v_lshl_add_u64 v[212:213], s[50:51], 0, v[136:137]
	s_add_i32 m0, s49, 0x2000
	s_nop 0
	global_load_lds_dwordx4 v[212:213], off
	v_lshl_add_u64 v[212:213], s[24:25], 0, v[132:133]
	s_mov_b32 m0, s5
	s_nop 0
	global_load_lds_dwordx4 v[212:213], off
	s_mov_b32 m0, s7
	s_nop 0
	global_load_lds_dwordx4 v[220:221], off
	s_waitcnt vmcnt(8)
	s_waitcnt lgkmcnt(0)
	s_barrier
; #define PG8_STAGE(bufoff, gbase, voff) do { _Pragma("unroll") for (int _i = 0; _i < 2; ++_i) \
;         __builtin_amdgcn_global_load_lds((const unsigned*)((const char*)(gbase) + (voff)[_i]), (PG8_LAS unsigned*)(lds + (bufoff) + ldsw + _i * 8192), 16, 0, 0); } while (0)
; #define PG8_LDA(dst, b, h) do { _Pragma("unroll") for (int m = 0; m < 4; ++m) _Pragma("unroll") for (int k = 0; k < 2; ++k) dst[m][k] = *(const PG8_LAS bf16x8*)(lds + PG8_SA(b, h) + aoffk[k] + m * 2048); } while (0)
; #define PG8_LDB(dst, b, h) do { _Pragma("unroll") for (int n = 0; n < 2; ++n) _Pragma("unroll") for (int k = 0; k < 2; ++k) dst[n][k] = *(const PG8_LAS bf16x8*)(lds + PG8_SB(b, h) + boffk[k] + n * 2048); } while (0)
; #define PG8_MMA(ai, bj, At, Bt) do { __builtin_amdgcn_s_setprio(1); _Pragma("unroll") for (int m = 0; m < 4; ++m) _Pragma("unroll") for (int n = 0; n < 2; ++n) _Pragma("unroll") for (int k = 0; k < 2; ++k) \
;         acc[ai][bj][m][n] = __builtin_amdgcn_mfma_f32_16x16x32_bf16(Bt[n][k], At[m][k], acc[ai][bj][m][n], 0, 0, 0); __builtin_amdgcn_s_setprio(0); } while (0)
; #define PG8_WAIT_V(n) asm volatile("s_waitcnt vmcnt(" #n ")" ::: "memory")
; #define PG8_WAIT_L(n) asm volatile("s_waitcnt lgkmcnt(" #n ")" ::: "memory")
; #define PG8_BAR __builtin_amdgcn_s_barrier()
; #define PG8_SCHED __builtin_amdgcn_sched_barrier(0)
; template <class Epi, class Sched, bool ALIGN_EPI = false, bool SP2 = false>
; __device__ __forceinline__ void gemm_phase(PG8_LAS unsigned char* lds, const Gemm g, const Sched& S, const Epi& E) {
;     ...
;             PG8_LDA(At, 0, 1); PG8_STAGE(PG8_SB(0, 0), b2, voffB); PG8_STAGE(PG8_SB(0, 1), b2 + hstepB, voffB); PG8_STAGE(PG8_SA(0, 0), a2, voffA);
;             PG8_WAIT_V(8); PG8_WAIT_L(0); PG8_BAR; PG8_MMA(1, 0, At, B0); PG8_MMA(1, 1, At, B1); PG8_BAR; PG8_SCHED;
;             PG8_LDB(B0, 1, 0); PG8_LDB(B1, 1, 1); PG8_SCHED; PG8_LDA(At, 1, 0); PG8_STAGE(PG8_SA(0, 1), a2 + hstepA, voffA);
;             PG8_WAIT_V(8); PG8_WAIT_L(0); PG8_BAR; PG8_MMA(0, 0, At, B0); PG8_MMA(0, 1, At, B1); PG8_BAR; PG8_SCHED;
	v_mfma_f32_16x16x32_bf16 v[64:67], v[150:153], v[188:191], 0
	v_mfma_f32_16x16x32_bf16 v[60:63], v[158:161], v[188:191], 0
	v_mfma_f32_16x16x32_bf16 v[56:59], v[150:153], v[196:199], 0
	v_mfma_f32_16x16x32_bf16 v[48:51], v[158:161], v[196:199], 0
	v_mfma_f32_16x16x32_bf16 v[40:43], v[150:153], v[204:207], 0
	v_mfma_f32_16x16x32_bf16 v[32:35], v[158:161], v[204:207], 0
	v_mfma_f32_16x16x32_bf16 v[24:27], v[150:153], v[226:229], 0
	v_mfma_f32_16x16x32_bf16 v[16:19], v[158:161], v[226:229], 0
	v_mfma_f32_16x16x32_bf16 v[64:67], v[154:157], v[192:195], v[64:67]
	v_mfma_f32_16x16x32_bf16 v[60:63], v[162:165], v[192:195], v[60:63]
	v_mfma_f32_16x16x32_bf16 v[56:59], v[154:157], v[200:203], v[56:59]
	v_mfma_f32_16x16x32_bf16 v[48:51], v[162:165], v[200:203], v[48:51]
	v_mfma_f32_16x16x32_bf16 v[40:43], v[154:157], v[208:211], v[40:43]
	v_mfma_f32_16x16x32_bf16 v[32:35], v[162:165], v[208:211], v[32:35]
	v_mfma_f32_16x16x32_bf16 v[24:27], v[154:157], v[230:233], v[24:27]
	v_mfma_f32_16x16x32_bf16 v[16:19], v[162:165], v[230:233], v[16:19]
	v_mfma_f32_16x16x32_bf16 v[52:55], v[172:175], v[188:191], 0
	v_mfma_f32_16x16x32_bf16 v[44:47], v[180:183], v[188:191], 0
	v_mfma_f32_16x16x32_bf16 v[36:39], v[172:175], v[196:199], 0
	v_mfma_f32_16x16x32_bf16 v[28:31], v[180:183], v[196:199], 0
	v_mfma_f32_16x16x32_bf16 v[20:23], v[172:175], v[204:207], 0
	v_mfma_f32_16x16x32_bf16 v[12:15], v[180:183], v[204:207], 0
	v_mfma_f32_16x16x32_bf16 v[8:11], v[172:175], v[226:229], 0
	v_mfma_f32_16x16x32_bf16 v[4:7], v[180:183], v[226:229], 0
	v_mfma_f32_16x16x32_bf16 v[52:55], v[176:179], v[192:195], v[52:55]
	v_mfma_f32_16x16x32_bf16 v[44:47], v[184:187], v[192:195], v[44:47]
	v_mfma_f32_16x16x32_bf16 v[36:39], v[176:179], v[200:203], v[36:39]
	v_mfma_f32_16x16x32_bf16 v[28:31], v[184:187], v[200:203], v[28:31]
	v_mfma_f32_16x16x32_bf16 v[20:23], v[176:179], v[208:211], v[20:23]
	v_mfma_f32_16x16x32_bf16 v[12:15], v[184:187], v[208:211], v[12:15]
	v_mfma_f32_16x16x32_bf16 v[8:11], v[176:179], v[230:233], v[8:11]
	v_mfma_f32_16x16x32_bf16 v[4:7], v[184:187], v[230:233], v[4:7]
	s_barrier
	s_add_i32 s49, 0, 0x18000
	v_add_u32_e32 v149, s49, v145
	v_add_u32_e32 v154, s49, v146
	ds_read_b128 v[150:153], v149
	ds_read_b128 v[154:157], v154
	v_add_u32_e32 v149, s55, v145
	v_add_u32_e32 v162, s55, v146
	s_add_i32 s50, 0, 0x1c000
	ds_read_b128 v[158:161], v149
	ds_read_b128 v[162:165], v162
	v_add_u32_e32 v149, s50, v145
	v_add_u32_e32 v168, s50, v146
	ds_read_b128 v[172:175], v149
	ds_read_b128 v[176:179], v168
	v_add_u32_e32 v149, s56, v145
	v_add_u32_e32 v168, s56, v146
	ds_read_b128 v[180:183], v149
	ds_read_b128 v[184:187], v168
	s_add_u32 s24, s24, 0x80000
	s_addc_u32 s25, s25, 0
	s_mov_b32 m0, s34
	v_lshl_add_u64 v[234:235], s[24:25], 0, v[132:133]
	ds_read_b128 v[188:191], v148 offset:32768
	ds_read_b128 v[192:195], v148 offset:33792
	ds_read_b128 v[196:199], v148 offset:34816
	ds_read_b128 v[200:203], v148 offset:35840
	ds_read_b128 v[204:207], v148 offset:36864
	ds_read_b128 v[208:211], v148 offset:37888
	ds_read_b128 v[226:229], v148 offset:38912
	ds_read_b128 v[230:233], v148 offset:39936
	global_load_lds_dwordx4 v[234:235], off
	v_lshl_add_u64 v[234:235], s[24:25], 0, v[134:135]
	s_mov_b32 m0, s35
	s_nop 0
	global_load_lds_dwordx4 v[234:235], off
	s_waitcnt vmcnt(8)
	s_waitcnt lgkmcnt(0)
	s_barrier
	v_mfma_f32_16x16x32_bf16 v[128:131], v[150:153], v[188:191], v[128:131]
	v_mfma_f32_16x16x32_bf16 v[124:127], v[158:161], v[188:191], v[124:127]
	v_mfma_f32_16x16x32_bf16 v[120:123], v[150:153], v[196:199], v[120:123]
	v_mfma_f32_16x16x32_bf16 v[112:115], v[158:161], v[196:199], v[112:115]
	v_mfma_f32_16x16x32_bf16 v[104:107], v[150:153], v[204:207], v[104:107]
	v_mfma_f32_16x16x32_bf16 v[96:99], v[158:161], v[204:207], v[96:99]
	v_mfma_f32_16x16x32_bf16 v[88:91], v[150:153], v[226:229], v[88:91]
	v_mfma_f32_16x16x32_bf16 v[80:83], v[158:161], v[226:229], v[80:83]
	v_mfma_f32_16x16x32_bf16 v[128:131], v[154:157], v[192:195], v[128:131]
	v_mfma_f32_16x16x32_bf16 v[124:127], v[162:165], v[192:195], v[124:127]
	v_mfma_f32_16x16x32_bf16 v[120:123], v[154:157], v[200:203], v[120:123]
	v_mfma_f32_16x16x32_bf16 v[112:115], v[162:165], v[200:203], v[112:115]
	v_mfma_f32_16x16x32_bf16 v[104:107], v[154:157], v[208:211], v[104:107]
	v_mfma_f32_16x16x32_bf16 v[96:99], v[162:165], v[208:211], v[96:99]
	v_mfma_f32_16x16x32_bf16 v[88:91], v[154:157], v[230:233], v[88:91]
	v_mfma_f32_16x16x32_bf16 v[80:83], v[162:165], v[230:233], v[80:83]
	v_mfma_f32_16x16x32_bf16 v[116:119], v[172:175], v[188:191], v[116:119]
	v_mfma_f32_16x16x32_bf16 v[108:111], v[180:183], v[188:191], v[108:111]
	v_mfma_f32_16x16x32_bf16 v[100:103], v[172:175], v[196:199], v[100:103]
	v_mfma_f32_16x16x32_bf16 v[92:95], v[180:183], v[196:199], v[92:95]
	v_mfma_f32_16x16x32_bf16 v[84:87], v[172:175], v[204:207], v[84:87]
	v_mfma_f32_16x16x32_bf16 v[76:79], v[180:183], v[204:207], v[76:79]
	v_mfma_f32_16x16x32_bf16 v[72:75], v[172:175], v[226:229], v[72:75]
	v_mfma_f32_16x16x32_bf16 v[68:71], v[180:183], v[226:229], v[68:71]
	v_mfma_f32_16x16x32_bf16 v[116:119], v[176:179], v[192:195], v[116:119]
	v_mfma_f32_16x16x32_bf16 v[108:111], v[184:187], v[192:195], v[108:111]
	v_mfma_f32_16x16x32_bf16 v[100:103], v[176:179], v[200:203], v[100:103]
	v_mfma_f32_16x16x32_bf16 v[92:95], v[184:187], v[200:203], v[92:95]
	v_mfma_f32_16x16x32_bf16 v[84:87], v[176:179], v[208:211], v[84:87]
	v_mfma_f32_16x16x32_bf16 v[76:79], v[184:187], v[208:211], v[76:79]
	v_mfma_f32_16x16x32_bf16 v[72:75], v[176:179], v[230:233], v[72:75]
	v_mfma_f32_16x16x32_bf16 v[68:71], v[184:187], v[230:233], v[68:71]
	s_barrier
; #define PG8_STAGE(bufoff, gbase, voff) do { _Pragma("unroll") for (int _i = 0; _i < 2; ++_i) \
;         __builtin_amdgcn_global_load_lds((const unsigned*)((const char*)(gbase) + (voff)[_i]), (PG8_LAS unsigned*)(lds + (bufoff) + ldsw + _i * 8192), 16, 0, 0); } while (0)
; #define PG8_LDA(dst, b, h) do { _Pragma("unroll") for (int m = 0; m < 4; ++m) _Pragma("unroll") for (int k = 0; k < 2; ++k) dst[m][k] = *(const PG8_LAS bf16x8*)(lds + PG8_SA(b, h) + aoffk[k] + m * 2048); } while (0)
; #define PG8_MMA(ai, bj, At, Bt) do { __builtin_amdgcn_s_setprio(1); _Pragma("unroll") for (int m = 0; m < 4; ++m) _Pragma("unroll") for (int n = 0; n < 2; ++n) _Pragma("unroll") for (int k = 0; k < 2; ++k) \
;         acc[ai][bj][m][n] = __builtin_amdgcn_mfma_f32_16x16x32_bf16(Bt[n][k], At[m][k], acc[ai][bj][m][n], 0, 0, 0); __builtin_amdgcn_s_setprio(0); } while (0)
; #define PG8_WAIT_V(n) asm volatile("s_waitcnt vmcnt(" #n ")" ::: "memory")
; #define PG8_WAIT_L(n) asm volatile("s_waitcnt lgkmcnt(" #n ")" ::: "memory")
; #define PG8_BAR __builtin_amdgcn_s_barrier()
; #define PG8_SCHED __builtin_amdgcn_sched_barrier(0)
; template <class Epi, class Sched, bool ALIGN_EPI = false, bool SP2 = false>
; __device__ __forceinline__ void gemm_phase(PG8_LAS unsigned char* lds, const Gemm g, const Sched& S, const Epi& E) {
;     ...
;         for (int t = 0; t < nt; t += 2) {
;             const bool last = (t == nt - 2);
;             const char* a1 = cA + (size_t)(t + 1) * kstep;
;             const char* a2 = last ? nA : cA + (size_t)(t + 2) * kstep; const char* b2 = last ? nB : cB + (size_t)(t + 2) * kstep;
;             const char* a3 = a2 + kstep; const char* b3 = b2 + kstep;
;     ...
;             PG8_LDA(At, 1, 1); PG8_STAGE(PG8_SB(1, 0), b3, voffB); PG8_STAGE(PG8_SB(1, 1), b3 + hstepB, voffB); PG8_STAGE(PG8_SA(1, 0), a3, voffA);
;             PG8_WAIT_V(8); PG8_WAIT_L(0); PG8_BAR; PG8_MMA(1, 0, At, B0); PG8_MMA(1, 1, At, B1); PG8_BAR; PG8_SCHED;
	s_add_i32 s24, s49, s33
	v_lshl_add_u64 v[142:143], v[142:143], 0, s[58:59]
	s_mov_b32 m0, s24
	ds_read_b128 v[188:191], v148 offset:49152
	ds_read_b128 v[192:195], v148 offset:50176
	ds_read_b128 v[196:199], v148 offset:51200
	ds_read_b128 v[200:203], v148 offset:52224
	ds_read_b128 v[204:207], v148 offset:53248
	ds_read_b128 v[208:211], v148 offset:54272
	ds_read_b128 v[226:229], v148 offset:55296
	ds_read_b128 v[230:233], v148 offset:56320
	global_load_lds_dwordx4 v[142:143], off
	s_add_i32 m0, s24, 0x2000
	s_add_u32 s22, s22, 0x80080
	v_lshl_add_u64 v[142:143], v[166:167], 0, s[58:59]
	s_addc_u32 s23, s23, 0
	s_add_i32 s24, s50, s33
	global_load_lds_dwordx4 v[142:143], off
	v_lshl_add_u64 v[142:143], s[22:23], 0, v[2:3]
	s_mov_b32 m0, s24
	s_nop 0
	global_load_lds_dwordx4 v[142:143], off
	v_lshl_add_u64 v[142:143], s[22:23], 0, v[136:137]
	s_add_i32 m0, s24, 0x2000
	s_nop 0
	global_load_lds_dwordx4 v[142:143], off
	v_lshl_add_u64 v[142:143], v[212:213], 0, s[58:59]
	s_mov_b32 m0, s40
	s_nop 0
	global_load_lds_dwordx4 v[142:143], off
	v_lshl_add_u64 v[142:143], v[220:221], 0, s[58:59]
	s_mov_b32 m0, s41
	s_nop 0
	global_load_lds_dwordx4 v[142:143], off
	s_waitcnt vmcnt(8)
	s_waitcnt lgkmcnt(0)
	s_barrier
	v_mfma_f32_16x16x32_bf16 v[64:67], v[150:153], v[188:191], v[64:67]
	v_mfma_f32_16x16x32_bf16 v[60:63], v[158:161], v[188:191], v[60:63]
	v_mfma_f32_16x16x32_bf16 v[56:59], v[150:153], v[196:199], v[56:59]
	v_mfma_f32_16x16x32_bf16 v[48:51], v[158:161], v[196:199], v[48:51]
	v_mfma_f32_16x16x32_bf16 v[40:43], v[150:153], v[204:207], v[40:43]
	v_mfma_f32_16x16x32_bf16 v[32:35], v[158:161], v[204:207], v[32:35]
	v_mfma_f32_16x16x32_bf16 v[24:27], v[150:153], v[226:229], v[24:27]
	v_mfma_f32_16x16x32_bf16 v[16:19], v[158:161], v[226:229], v[16:19]
	v_mfma_f32_16x16x32_bf16 v[64:67], v[154:157], v[192:195], v[64:67]
	v_mfma_f32_16x16x32_bf16 v[60:63], v[162:165], v[192:195], v[60:63]
	v_mfma_f32_16x16x32_bf16 v[56:59], v[154:157], v[200:203], v[56:59]
	v_mfma_f32_16x16x32_bf16 v[48:51], v[162:165], v[200:203], v[48:51]
	v_mfma_f32_16x16x32_bf16 v[40:43], v[154:157], v[208:211], v[40:43]
	v_mfma_f32_16x16x32_bf16 v[32:35], v[162:165], v[208:211], v[32:35]
	v_mfma_f32_16x16x32_bf16 v[24:27], v[154:157], v[230:233], v[24:27]
	v_mfma_f32_16x16x32_bf16 v[16:19], v[162:165], v[230:233], v[16:19]
	v_mfma_f32_16x16x32_bf16 v[52:55], v[172:175], v[188:191], v[52:55]
	v_mfma_f32_16x16x32_bf16 v[44:47], v[180:183], v[188:191], v[44:47]
	v_mfma_f32_16x16x32_bf16 v[36:39], v[172:175], v[196:199], v[36:39]
	v_mfma_f32_16x16x32_bf16 v[28:31], v[180:183], v[196:199], v[28:31]
	v_mfma_f32_16x16x32_bf16 v[20:23], v[172:175], v[204:207], v[20:23]
	v_mfma_f32_16x16x32_bf16 v[12:15], v[180:183], v[204:207], v[12:15]
	v_mfma_f32_16x16x32_bf16 v[8:11], v[172:175], v[226:229], v[8:11]
	v_mfma_f32_16x16x32_bf16 v[4:7], v[180:183], v[226:229], v[4:7]
	v_mfma_f32_16x16x32_bf16 v[52:55], v[176:179], v[192:195], v[52:55]
	v_mfma_f32_16x16x32_bf16 v[44:47], v[184:187], v[192:195], v[44:47]
	v_mfma_f32_16x16x32_bf16 v[36:39], v[176:179], v[200:203], v[36:39]
	v_mfma_f32_16x16x32_bf16 v[28:31], v[184:187], v[200:203], v[28:31]
	v_mfma_f32_16x16x32_bf16 v[20:23], v[176:179], v[208:211], v[20:23]
	v_mfma_f32_16x16x32_bf16 v[12:15], v[184:187], v[208:211], v[12:15]
	v_mfma_f32_16x16x32_bf16 v[8:11], v[176:179], v[230:233], v[8:11]
	v_mfma_f32_16x16x32_bf16 v[4:7], v[184:187], v[230:233], v[4:7]
	s_barrier
	s_add_u32 s20, s20, 0x100
	s_addc_u32 s21, s21, 0
	s_add_u32 s13, s13, 0x100
	s_addc_u32 s15, s15, 0
	s_cmp_ge_i32 s48, s45
	s_mov_b32 s22, s48
	s_cbranch_scc0 .LBB0_1293
	s_branch .Lgemm_after_3

; #define PG8_BAR __builtin_amdgcn_s_barrier()
; template <class Epi, class Sched, bool ALIGN_EPI = false, bool SP2 = false>
; __device__ __forceinline__ void gemm_phase(PG8_LAS unsigned char* lds, const Gemm g, const Sched& S, const Epi& E) {
;     ...
;         if constexpr (ALIGN_EPI) { if (wr == 0) PG8_BAR; }
.Lgemm_after_3:
	s_and_b64 vcc, exec, s[8:9]
	s_cbranch_vccz .LBB0_1296
	s_barrier

; #define PG8_STAGE(bufoff, gbase, voff) do { _Pragma("unroll") for (int _i = 0; _i < 2; ++_i) \
;         __builtin_amdgcn_global_load_lds((const unsigned*)((const char*)(gbase) + (voff)[_i]), (PG8_LAS unsigned*)(lds + (bufoff) + ldsw + _i * 8192), 16, 0, 0); } while (0)
; #define PG8_LDA(dst, b, h) do { _Pragma("unroll") for (int m = 0; m < 4; ++m) _Pragma("unroll") for (int k = 0; k < 2; ++k) dst[m][k] = *(const PG8_LAS bf16x8*)(lds + PG8_SA(b, h) + aoffk[k] + m * 2048); } while (0)
; #define PG8_WAIT_V(n) asm volatile("s_waitcnt vmcnt(" #n ")" ::: "memory")
; #define PG8_BAR __builtin_amdgcn_s_barrier()
; template <class Epi, class Sched, bool ALIGN_EPI = false, bool SP2 = false>
; __device__ __forceinline__ void gemm_phase(PG8_LAS unsigned char* lds, const Gemm g, const Sched& S, const Epi& E) {
;     ...
;     f32x4 acc[2][2][4][2];
; #pragma unroll
;     for (int a = 0; a < 2; ++a)
; #pragma unroll
;         for (int b = 0; b < 2; ++b)
; #pragma unroll
;             for (int m = 0; m < 4; ++m)
; #pragma unroll
;                 for (int n = 0; n < 2; ++n) acc[a][b][m][n] = (f32x4){0.f, 0.f, 0.f, 0.f};
;     ...
;         const bool has_next = S.next(ui + 1, nxt);
;         const char* nA = has_next ? (const char*)g.A + (size_t)nxt.pm * tstepA + (size_t)nxt.kt0 * kstep : cA; const char* nB = has_next ? (const char*)g.Bt + (size_t)nxt.pn * tstepB + (size_t)nxt.kt0 * kstep : cB;
;         const int nt = cur.nt;
;         for (int t = 0; t < nt; t += 2) {
;             const bool last = (t == nt - 2);
;             const char* a1 = cA + (size_t)(t + 1) * kstep;
;             const char* a2 = last ? nA : cA + (size_t)(t + 2) * kstep; const char* b2 = last ? nB : cB + (size_t)(t + 2) * kstep;
;             const char* a3 = a2 + kstep; const char* b3 = b2 + kstep;
;             if (last && has_next) S.a_ready(nxt);
;             if constexpr (SP2) {
;             PG8_LDB(B0, 0, 0); PG8_LDB(B1, 0, 1); PG8_SCHED; PG8_LDA(At, 0, 0); PG8_STAGE(PG8_SA(1, 1), a1 + hstepA, voffA);
;             PG8_WAIT_V(8); PG8_WAIT_L(0); PG8_BAR; PG8_MMA(0, 0, At, B0); PG8_MMA(0, 1, At, B1); PG8_BAR; PG8_SCHED;
;             PG8_LDA(At, 0, 1); PG8_STAGE(PG8_SB(0, 0), b2, voffB); PG8_STAGE(PG8_SB(0, 1), b2 + hstepB, voffB); PG8_STAGE(PG8_SA(0, 0), a2, voffA);
;             PG8_WAIT_V(8); PG8_WAIT_L(0); PG8_BAR; PG8_MMA(1, 0, At, B0); PG8_MMA(1, 1, At, B1); PG8_BAR; PG8_SCHED;
.LBB0_1431:
	s_ashr_i32 s9, s8, 31
	s_lshl_b64 s[12:13], s[8:9], 20
	s_add_u32 s12, s27, s12
	s_addc_u32 s13, s28, s13
	s_and_b64 s[14:15], s[10:11], exec
	s_cselect_b32 s9, s13, s19
	s_cselect_b32 s33, s12, s18
	s_ashr_i32 s7, s6, 31
	s_lshl_b64 s[14:15], s[6:7], 20
	s_add_u32 s14, s29, s14
	s_addc_u32 s15, s30, s15
	s_and_b64 s[22:23], s[10:11], exec
	s_cselect_b32 s7, s15, s21
	s_cselect_b32 s43, s14, s20
	s_add_u32 s18, s18, 0x80080
	s_addc_u32 s19, s19, 0
	s_add_u32 s44, s20, 0x100
	s_addc_u32 s45, s21, 0
	s_mov_b32 s46, -2
	v_readlane_b32 s51, v253, 28
	v_readlane_b32 s52, v253, 29
	v_readlane_b32 s53, v253, 30
	v_readlane_b32 s54, v253, 31
	s_mov_b64 s[56:57], 0x80
.Lgemm_first_4:
	s_add_u32 s20, s18, 0xfff80080
	s_addc_u32 s21, s19, -1
	s_add_i32 s47, 0, 0x10000
	s_cmp_eq_u32 s46, 28
	v_add_u32_e32 v142, s47, v147
	v_add_u32_e32 v151, s47, v148
	s_cselect_b32 s23, s9, s21
	s_cselect_b32 s22, s33, s20
	ds_read_b128 v[142:145], v142
	ds_read_b128 v[152:155], v151
	v_add_u32_e32 v151, s51, v147
	v_add_u32_e32 v160, s51, v148
	s_cselect_b32 s21, s7, s45
	s_cselect_b32 s20, s43, s44
	s_add_i32 s50, 0, 0x14000
	ds_read_b128 v[156:159], v151
	ds_read_b128 v[160:163], v160
	v_add_u32_e32 v151, s50, v147
	v_add_u32_e32 v168, s50, v148
	ds_read_b128 v[164:167], v151
	ds_read_b128 v[172:175], v168
	v_add_u32_e32 v151, s52, v147
	v_add_u32_e32 v168, s52, v148
	ds_read_b128 v[176:179], v151
	ds_read_b128 v[180:183], v168
	v_lshl_add_u64 v[212:213], s[18:19], 0, v[138:139]
	s_add_i32 m0, s36, 0xc000
	ds_read_b128 v[184:187], v150
	ds_read_b128 v[188:191], v150 offset:1024
	ds_read_b128 v[192:195], v150 offset:2048
	ds_read_b128 v[196:199], v150 offset:3072
	ds_read_b128 v[200:203], v150 offset:4096
	ds_read_b128 v[204:207], v150 offset:5120
	ds_read_b128 v[208:211], v150 offset:6144
	ds_read_b128 v[226:229], v150 offset:7168
	global_load_lds_dwordx4 v[212:213], off
	v_lshl_add_u64 v[212:213], s[18:19], 0, v[140:141]
	s_add_i32 m0, s36, 0xe000
	s_nop 0
	global_load_lds_dwordx4 v[212:213], off
	s_waitcnt vmcnt(8)
	s_waitcnt lgkmcnt(0)
	s_barrier
	v_mfma_f32_16x16x32_bf16 v[128:131], v[142:145], v[184:187], 0
	v_mfma_f32_16x16x32_bf16 v[120:123], v[156:159], v[184:187], 0
	v_mfma_f32_16x16x32_bf16 v[112:115], v[142:145], v[192:195], 0
	v_mfma_f32_16x16x32_bf16 v[104:107], v[156:159], v[192:195], 0
	v_mfma_f32_16x16x32_bf16 v[96:99], v[142:145], v[200:203], 0
	v_mfma_f32_16x16x32_bf16 v[88:91], v[156:159], v[200:203], 0
	v_mfma_f32_16x16x32_bf16 v[80:83], v[142:145], v[208:211], 0
	v_mfma_f32_16x16x32_bf16 v[72:75], v[156:159], v[208:211], 0
	v_mfma_f32_16x16x32_bf16 v[128:131], v[152:155], v[188:191], v[128:131]
	v_mfma_f32_16x16x32_bf16 v[120:123], v[160:163], v[188:191], v[120:123]
	v_mfma_f32_16x16x32_bf16 v[112:115], v[152:155], v[196:199], v[112:115]
	v_mfma_f32_16x16x32_bf16 v[104:107], v[160:163], v[196:199], v[104:107]
	v_mfma_f32_16x16x32_bf16 v[96:99], v[152:155], v[204:207], v[96:99]
	v_mfma_f32_16x16x32_bf16 v[88:91], v[160:163], v[204:207], v[88:91]
	v_mfma_f32_16x16x32_bf16 v[80:83], v[152:155], v[226:229], v[80:83]
	v_mfma_f32_16x16x32_bf16 v[72:75], v[160:163], v[226:229], v[72:75]
	v_mfma_f32_16x16x32_bf16 v[124:127], v[164:167], v[184:187], 0
	v_mfma_f32_16x16x32_bf16 v[116:119], v[176:179], v[184:187], 0
	v_mfma_f32_16x16x32_bf16 v[108:111], v[164:167], v[192:195], 0
	v_mfma_f32_16x16x32_bf16 v[100:103], v[176:179], v[192:195], 0
	v_mfma_f32_16x16x32_bf16 v[92:95], v[164:167], v[200:203], 0
	v_mfma_f32_16x16x32_bf16 v[84:87], v[176:179], v[200:203], 0
	v_mfma_f32_16x16x32_bf16 v[76:79], v[164:167], v[208:211], 0
	v_mfma_f32_16x16x32_bf16 v[68:71], v[176:179], v[208:211], 0
	v_mfma_f32_16x16x32_bf16 v[124:127], v[172:175], v[188:191], v[124:127]
	v_mfma_f32_16x16x32_bf16 v[116:119], v[180:183], v[188:191], v[116:119]
	v_mfma_f32_16x16x32_bf16 v[108:111], v[172:175], v[196:199], v[108:111]
	v_mfma_f32_16x16x32_bf16 v[100:103], v[180:183], v[196:199], v[100:103]
	v_mfma_f32_16x16x32_bf16 v[92:95], v[172:175], v[204:207], v[92:95]
	v_mfma_f32_16x16x32_bf16 v[84:87], v[180:183], v[204:207], v[84:87]
	v_mfma_f32_16x16x32_bf16 v[76:79], v[172:175], v[226:229], v[76:79]
	v_mfma_f32_16x16x32_bf16 v[68:71], v[180:183], v[226:229], v[68:71]
	s_barrier
	s_add_i32 s47, s47, s31
	v_lshl_add_u64 v[212:213], s[20:21], 0, v[2:3]
	s_mov_b32 m0, s47
	ds_read_b128 v[184:187], v150 offset:16384
	ds_read_b128 v[188:191], v150 offset:17408
	ds_read_b128 v[192:195], v150 offset:18432
	ds_read_b128 v[196:199], v150 offset:19456
	ds_read_b128 v[200:203], v150 offset:20480
	ds_read_b128 v[204:207], v150 offset:21504
	ds_read_b128 v[208:211], v150 offset:22528
	ds_read_b128 v[226:229], v150 offset:23552
	global_load_lds_dwordx4 v[212:213], off
	s_add_i32 m0, s47, 0x2000
	s_add_u32 s48, s20, 0x80000
	v_lshl_add_u64 v[220:221], s[20:21], 0, v[132:133]
	s_addc_u32 s49, s21, 0
	s_add_i32 s47, s50, s31
	global_load_lds_dwordx4 v[220:221], off
	v_lshl_add_u64 v[230:231], s[48:49], 0, v[2:3]
	s_mov_b32 m0, s47
	v_lshl_add_u64 v[232:233], s[22:23], 0, v[134:135]
	global_load_lds_dwordx4 v[230:231], off
	v_lshl_add_u64 v[230:231], s[48:49], 0, v[132:133]
	s_add_i32 m0, s47, 0x2000
	s_nop 0
	global_load_lds_dwordx4 v[230:231], off
	v_lshl_add_u64 v[230:231], s[22:23], 0, v[136:137]
	s_mov_b32 m0, s36
	s_nop 0
	global_load_lds_dwordx4 v[230:231], off
	s_mov_b32 m0, s37
	s_nop 0
	global_load_lds_dwordx4 v[232:233], off
	s_waitcnt vmcnt(8)
	s_waitcnt lgkmcnt(0)
	s_barrier
; #define PG8_STAGE(bufoff, gbase, voff) do { _Pragma("unroll") for (int _i = 0; _i < 2; ++_i) \
;         __builtin_amdgcn_global_load_lds((const unsigned*)((const char*)(gbase) + (voff)[_i]), (PG8_LAS unsigned*)(lds + (bufoff) + ldsw + _i * 8192), 16, 0, 0); } while (0)
; #define PG8_LDA(dst, b, h) do { _Pragma("unroll") for (int m = 0; m < 4; ++m) _Pragma("unroll") for (int k = 0; k < 2; ++k) dst[m][k] = *(const PG8_LAS bf16x8*)(lds + PG8_SA(b, h) + aoffk[k] + m * 2048); } while (0)
; #define PG8_LDB(dst, b, h) do { _Pragma("unroll") for (int n = 0; n < 2; ++n) _Pragma("unroll") for (int k = 0; k < 2; ++k) dst[n][k] = *(const PG8_LAS bf16x8*)(lds + PG8_SB(b, h) + boffk[k] + n * 2048); } while (0)
; #define PG8_MMA(ai, bj, At, Bt) do { __builtin_amdgcn_s_setprio(1); _Pragma("unroll") for (int m = 0; m < 4; ++m) _Pragma("unroll") for (int n = 0; n < 2; ++n) _Pragma("unroll") for (int k = 0; k < 2; ++k) \
;         acc[ai][bj][m][n] = __builtin_amdgcn_mfma_f32_16x16x32_bf16(Bt[n][k], At[m][k], acc[ai][bj][m][n], 0, 0, 0); __builtin_amdgcn_s_setprio(0); } while (0)
; #define PG8_WAIT_V(n) asm volatile("s_waitcnt vmcnt(" #n ")" ::: "memory")
; #define PG8_WAIT_L(n) asm volatile("s_waitcnt lgkmcnt(" #n ")" ::: "memory")
; #define PG8_BAR __builtin_amdgcn_s_barrier()
; #define PG8_SCHED __builtin_amdgcn_sched_barrier(0)
; template <class Epi, class Sched, bool ALIGN_EPI = false, bool SP2 = false>
; __device__ __forceinline__ void gemm_phase(PG8_LAS unsigned char* lds, const Gemm g, const Sched& S, const Epi& E) {
;     ...
;             PG8_LDA(At, 0, 1); PG8_STAGE(PG8_SB(0, 0), b2, voffB); PG8_STAGE(PG8_SB(0, 1), b2 + hstepB, voffB); PG8_STAGE(PG8_SA(0, 0), a2, voffA);
;             PG8_WAIT_V(8); PG8_WAIT_L(0); PG8_BAR; PG8_MMA(1, 0, At, B0); PG8_MMA(1, 1, At, B1); PG8_BAR; PG8_SCHED;
;             PG8_LDB(B0, 1, 0); PG8_LDB(B1, 1, 1); PG8_SCHED; PG8_LDA(At, 1, 0); PG8_STAGE(PG8_SA(0, 1), a2 + hstepA, voffA);
;             PG8_WAIT_V(8); PG8_WAIT_L(0); PG8_BAR; PG8_MMA(0, 0, At, B0); PG8_MMA(0, 1, At, B1); PG8_BAR; PG8_SCHED;
	v_mfma_f32_16x16x32_bf16 v[64:67], v[142:145], v[184:187], 0
	v_mfma_f32_16x16x32_bf16 v[56:59], v[156:159], v[184:187], 0
	v_mfma_f32_16x16x32_bf16 v[48:51], v[142:145], v[192:195], 0
	v_mfma_f32_16x16x32_bf16 v[40:43], v[156:159], v[192:195], 0
	v_mfma_f32_16x16x32_bf16 v[32:35], v[142:145], v[200:203], 0
	v_mfma_f32_16x16x32_bf16 v[24:27], v[156:159], v[200:203], 0
	v_mfma_f32_16x16x32_bf16 v[16:19], v[142:145], v[208:211], 0
	v_mfma_f32_16x16x32_bf16 v[8:11], v[156:159], v[208:211], 0
	v_mfma_f32_16x16x32_bf16 v[64:67], v[152:155], v[188:191], v[64:67]
	v_mfma_f32_16x16x32_bf16 v[56:59], v[160:163], v[188:191], v[56:59]
	v_mfma_f32_16x16x32_bf16 v[48:51], v[152:155], v[196:199], v[48:51]
	v_mfma_f32_16x16x32_bf16 v[40:43], v[160:163], v[196:199], v[40:43]
	v_mfma_f32_16x16x32_bf16 v[32:35], v[152:155], v[204:207], v[32:35]
	v_mfma_f32_16x16x32_bf16 v[24:27], v[160:163], v[204:207], v[24:27]
	v_mfma_f32_16x16x32_bf16 v[16:19], v[152:155], v[226:229], v[16:19]
	v_mfma_f32_16x16x32_bf16 v[8:11], v[160:163], v[226:229], v[8:11]
	v_mfma_f32_16x16x32_bf16 v[60:63], v[164:167], v[184:187], 0
	v_mfma_f32_16x16x32_bf16 v[52:55], v[176:179], v[184:187], 0
	v_mfma_f32_16x16x32_bf16 v[44:47], v[164:167], v[192:195], 0
	v_mfma_f32_16x16x32_bf16 v[36:39], v[176:179], v[192:195], 0
	v_mfma_f32_16x16x32_bf16 v[28:31], v[164:167], v[200:203], 0
	v_mfma_f32_16x16x32_bf16 v[20:23], v[176:179], v[200:203], 0
	v_mfma_f32_16x16x32_bf16 v[12:15], v[164:167], v[208:211], 0
	v_mfma_f32_16x16x32_bf16 v[4:7], v[176:179], v[208:211], 0
	v_mfma_f32_16x16x32_bf16 v[60:63], v[172:175], v[188:191], v[60:63]
	v_mfma_f32_16x16x32_bf16 v[52:55], v[180:183], v[188:191], v[52:55]
	v_mfma_f32_16x16x32_bf16 v[44:47], v[172:175], v[196:199], v[44:47]
	v_mfma_f32_16x16x32_bf16 v[36:39], v[180:183], v[196:199], v[36:39]
	v_mfma_f32_16x16x32_bf16 v[28:31], v[172:175], v[204:207], v[28:31]
	v_mfma_f32_16x16x32_bf16 v[20:23], v[180:183], v[204:207], v[20:23]
	v_mfma_f32_16x16x32_bf16 v[12:15], v[172:175], v[226:229], v[12:15]
	v_mfma_f32_16x16x32_bf16 v[4:7], v[180:183], v[226:229], v[4:7]
	s_barrier
	s_add_i32 s47, 0, 0x18000
	v_add_u32_e32 v142, s47, v147
	v_add_u32_e32 v151, s47, v148
	ds_read_b128 v[142:145], v142
	ds_read_b128 v[152:155], v151
	v_add_u32_e32 v151, s53, v147
	v_add_u32_e32 v160, s53, v148
	s_add_i32 s48, 0, 0x1c000
	ds_read_b128 v[156:159], v151
	ds_read_b128 v[160:163], v160
	v_add_u32_e32 v151, s48, v147
	v_add_u32_e32 v168, s48, v148
	ds_read_b128 v[164:167], v151
	ds_read_b128 v[172:175], v168
	v_add_u32_e32 v151, s54, v147
	v_add_u32_e32 v168, s54, v148
	ds_read_b128 v[176:179], v151
	ds_read_b128 v[180:183], v168
	s_add_u32 s22, s22, 0x80000
	s_addc_u32 s23, s23, 0
	s_mov_b32 m0, s38
	v_lshl_add_u64 v[234:235], s[22:23], 0, v[136:137]
	ds_read_b128 v[184:187], v150 offset:32768
	ds_read_b128 v[188:191], v150 offset:33792
	ds_read_b128 v[192:195], v150 offset:34816
	ds_read_b128 v[196:199], v150 offset:35840
	ds_read_b128 v[200:203], v150 offset:36864
	ds_read_b128 v[204:207], v150 offset:37888
	ds_read_b128 v[208:211], v150 offset:38912
	ds_read_b128 v[226:229], v150 offset:39936
	global_load_lds_dwordx4 v[234:235], off
	v_lshl_add_u64 v[234:235], s[22:23], 0, v[134:135]
	s_mov_b32 m0, s39
	s_nop 0
	global_load_lds_dwordx4 v[234:235], off
	s_waitcnt vmcnt(8)
	s_waitcnt lgkmcnt(0)
	s_barrier
	v_mfma_f32_16x16x32_bf16 v[128:131], v[142:145], v[184:187], v[128:131]
	v_mfma_f32_16x16x32_bf16 v[120:123], v[156:159], v[184:187], v[120:123]
	v_mfma_f32_16x16x32_bf16 v[112:115], v[142:145], v[192:195], v[112:115]
	v_mfma_f32_16x16x32_bf16 v[104:107], v[156:159], v[192:195], v[104:107]
	v_mfma_f32_16x16x32_bf16 v[96:99], v[142:145], v[200:203], v[96:99]
	v_mfma_f32_16x16x32_bf16 v[88:91], v[156:159], v[200:203], v[88:91]
	v_mfma_f32_16x16x32_bf16 v[80:83], v[142:145], v[208:211], v[80:83]
	v_mfma_f32_16x16x32_bf16 v[72:75], v[156:159], v[208:211], v[72:75]
	v_mfma_f32_16x16x32_bf16 v[128:131], v[152:155], v[188:191], v[128:131]
	v_mfma_f32_16x16x32_bf16 v[120:123], v[160:163], v[188:191], v[120:123]
	v_mfma_f32_16x16x32_bf16 v[112:115], v[152:155], v[196:199], v[112:115]
	v_mfma_f32_16x16x32_bf16 v[104:107], v[160:163], v[196:199], v[104:107]
	v_mfma_f32_16x16x32_bf16 v[96:99], v[152:155], v[204:207], v[96:99]
	v_mfma_f32_16x16x32_bf16 v[88:91], v[160:163], v[204:207], v[88:91]
	v_mfma_f32_16x16x32_bf16 v[80:83], v[152:155], v[226:229], v[80:83]
	v_mfma_f32_16x16x32_bf16 v[72:75], v[160:163], v[226:229], v[72:75]
	v_mfma_f32_16x16x32_bf16 v[124:127], v[164:167], v[184:187], v[124:127]
	v_mfma_f32_16x16x32_bf16 v[116:119], v[176:179], v[184:187], v[116:119]
	v_mfma_f32_16x16x32_bf16 v[108:111], v[164:167], v[192:195], v[108:111]
	v_mfma_f32_16x16x32_bf16 v[100:103], v[176:179], v[192:195], v[100:103]
	v_mfma_f32_16x16x32_bf16 v[92:95], v[164:167], v[200:203], v[92:95]
	v_mfma_f32_16x16x32_bf16 v[84:87], v[176:179], v[200:203], v[84:87]
	v_mfma_f32_16x16x32_bf16 v[76:79], v[164:167], v[208:211], v[76:79]
	v_mfma_f32_16x16x32_bf16 v[68:71], v[176:179], v[208:211], v[68:71]
	v_mfma_f32_16x16x32_bf16 v[124:127], v[172:175], v[188:191], v[124:127]
	v_mfma_f32_16x16x32_bf16 v[116:119], v[180:183], v[188:191], v[116:119]
	v_mfma_f32_16x16x32_bf16 v[108:111], v[172:175], v[196:199], v[108:111]
	v_mfma_f32_16x16x32_bf16 v[100:103], v[180:183], v[196:199], v[100:103]
	v_mfma_f32_16x16x32_bf16 v[92:95], v[172:175], v[204:207], v[92:95]
	v_mfma_f32_16x16x32_bf16 v[84:87], v[180:183], v[204:207], v[84:87]
	v_mfma_f32_16x16x32_bf16 v[76:79], v[172:175], v[226:229], v[76:79]
	v_mfma_f32_16x16x32_bf16 v[68:71], v[180:183], v[226:229], v[68:71]
	s_barrier
; #define PG8_STAGE(bufoff, gbase, voff) do { _Pragma("unroll") for (int _i = 0; _i < 2; ++_i) \
;         __builtin_amdgcn_global_load_lds((const unsigned*)((const char*)(gbase) + (voff)[_i]), (PG8_LAS unsigned*)(lds + (bufoff) + ldsw + _i * 8192), 16, 0, 0); } while (0)
; #define PG8_LDA(dst, b, h) do { _Pragma("unroll") for (int m = 0; m < 4; ++m) _Pragma("unroll") for (int k = 0; k < 2; ++k) dst[m][k] = *(const PG8_LAS bf16x8*)(lds + PG8_SA(b, h) + aoffk[k] + m * 2048); } while (0)
; #define PG8_MMA(ai, bj, At, Bt) do { __builtin_amdgcn_s_setprio(1); _Pragma("unroll") for (int m = 0; m < 4; ++m) _Pragma("unroll") for (int n = 0; n < 2; ++n) _Pragma("unroll") for (int k = 0; k < 2; ++k) \
;         acc[ai][bj][m][n] = __builtin_amdgcn_mfma_f32_16x16x32_bf16(Bt[n][k], At[m][k], acc[ai][bj][m][n], 0, 0, 0); __builtin_amdgcn_s_setprio(0); } while (0)
; #define PG8_WAIT_V(n) asm volatile("s_waitcnt vmcnt(" #n ")" ::: "memory")
; #define PG8_WAIT_L(n) asm volatile("s_waitcnt lgkmcnt(" #n ")" ::: "memory")
; #define PG8_BAR __builtin_amdgcn_s_barrier()
; #define PG8_SCHED __builtin_amdgcn_sched_barrier(0)
; template <class Epi, class Sched, bool ALIGN_EPI = false, bool SP2 = false>
; __device__ __forceinline__ void gemm_phase(PG8_LAS unsigned char* lds, const Gemm g, const Sched& S, const Epi& E) {
;     ...
;         for (int t = 0; t < nt; t += 2) {
;             const bool last = (t == nt - 2);
;             const char* a1 = cA + (size_t)(t + 1) * kstep;
;             const char* a2 = last ? nA : cA + (size_t)(t + 2) * kstep; const char* b2 = last ? nB : cB + (size_t)(t + 2) * kstep;
;             const char* a3 = a2 + kstep; const char* b3 = b2 + kstep;
;     ...
;             PG8_LDA(At, 1, 1); PG8_STAGE(PG8_SB(1, 0), b3, voffB); PG8_STAGE(PG8_SB(1, 1), b3 + hstepB, voffB); PG8_STAGE(PG8_SA(1, 0), a3, voffA);
;             PG8_WAIT_V(8); PG8_WAIT_L(0); PG8_BAR; PG8_MMA(1, 0, At, B0); PG8_MMA(1, 1, At, B1); PG8_BAR; PG8_SCHED;
	s_add_i32 s22, s47, s31
	v_lshl_add_u64 v[212:213], v[212:213], 0, s[56:57]
	s_mov_b32 m0, s22
	ds_read_b128 v[184:187], v150 offset:49152
	ds_read_b128 v[188:191], v150 offset:50176
	ds_read_b128 v[192:195], v150 offset:51200
	ds_read_b128 v[196:199], v150 offset:52224
	ds_read_b128 v[200:203], v150 offset:53248
	ds_read_b128 v[204:207], v150 offset:54272
	ds_read_b128 v[208:211], v150 offset:55296
	ds_read_b128 v[226:229], v150 offset:56320
	global_load_lds_dwordx4 v[212:213], off
	s_add_i32 m0, s22, 0x2000
	s_add_u32 s20, s20, 0x80080
	v_lshl_add_u64 v[212:213], v[220:221], 0, s[56:57]
	s_addc_u32 s21, s21, 0
	s_add_i32 s22, s48, s31
	global_load_lds_dwordx4 v[212:213], off
	v_lshl_add_u64 v[212:213], s[20:21], 0, v[2:3]
	s_mov_b32 m0, s22
	s_nop 0
	global_load_lds_dwordx4 v[212:213], off
	v_lshl_add_u64 v[212:213], s[20:21], 0, v[132:133]
	s_add_i32 m0, s22, 0x2000
	s_nop 0
	global_load_lds_dwordx4 v[212:213], off
	v_lshl_add_u64 v[212:213], v[230:231], 0, s[56:57]
	s_mov_b32 m0, s40
	s_nop 0
	global_load_lds_dwordx4 v[212:213], off
	v_lshl_add_u64 v[212:213], v[232:233], 0, s[56:57]
	s_mov_b32 m0, s41
	s_nop 0
	global_load_lds_dwordx4 v[212:213], off
	s_waitcnt vmcnt(8)
	s_waitcnt lgkmcnt(0)
	s_barrier
	v_mfma_f32_16x16x32_bf16 v[64:67], v[142:145], v[184:187], v[64:67]
	v_mfma_f32_16x16x32_bf16 v[56:59], v[156:159], v[184:187], v[56:59]
	v_mfma_f32_16x16x32_bf16 v[48:51], v[142:145], v[192:195], v[48:51]
	v_mfma_f32_16x16x32_bf16 v[40:43], v[156:159], v[192:195], v[40:43]
	v_mfma_f32_16x16x32_bf16 v[32:35], v[142:145], v[200:203], v[32:35]
	v_mfma_f32_16x16x32_bf16 v[24:27], v[156:159], v[200:203], v[24:27]
	v_mfma_f32_16x16x32_bf16 v[16:19], v[142:145], v[208:211], v[16:19]
	v_mfma_f32_16x16x32_bf16 v[8:11], v[156:159], v[208:211], v[8:11]
	v_mfma_f32_16x16x32_bf16 v[64:67], v[152:155], v[188:191], v[64:67]
	v_mfma_f32_16x16x32_bf16 v[56:59], v[160:163], v[188:191], v[56:59]
	v_mfma_f32_16x16x32_bf16 v[48:51], v[152:155], v[196:199], v[48:51]
	v_mfma_f32_16x16x32_bf16 v[40:43], v[160:163], v[196:199], v[40:43]
	v_mfma_f32_16x16x32_bf16 v[32:35], v[152:155], v[204:207], v[32:35]
	v_mfma_f32_16x16x32_bf16 v[24:27], v[160:163], v[204:207], v[24:27]
	v_mfma_f32_16x16x32_bf16 v[16:19], v[152:155], v[226:229], v[16:19]
	v_mfma_f32_16x16x32_bf16 v[8:11], v[160:163], v[226:229], v[8:11]
	v_mfma_f32_16x16x32_bf16 v[60:63], v[164:167], v[184:187], v[60:63]
	v_mfma_f32_16x16x32_bf16 v[52:55], v[176:179], v[184:187], v[52:55]
	v_mfma_f32_16x16x32_bf16 v[44:47], v[164:167], v[192:195], v[44:47]
	v_mfma_f32_16x16x32_bf16 v[36:39], v[176:179], v[192:195], v[36:39]
	v_mfma_f32_16x16x32_bf16 v[28:31], v[164:167], v[200:203], v[28:31]
	v_mfma_f32_16x16x32_bf16 v[20:23], v[176:179], v[200:203], v[20:23]
	v_mfma_f32_16x16x32_bf16 v[12:15], v[164:167], v[208:211], v[12:15]
	v_mfma_f32_16x16x32_bf16 v[4:7], v[176:179], v[208:211], v[4:7]
	v_mfma_f32_16x16x32_bf16 v[60:63], v[172:175], v[188:191], v[60:63]
	v_mfma_f32_16x16x32_bf16 v[52:55], v[180:183], v[188:191], v[52:55]
	v_mfma_f32_16x16x32_bf16 v[44:47], v[172:175], v[196:199], v[44:47]
	v_mfma_f32_16x16x32_bf16 v[36:39], v[180:183], v[196:199], v[36:39]
	v_mfma_f32_16x16x32_bf16 v[28:31], v[172:175], v[204:207], v[28:31]
	v_mfma_f32_16x16x32_bf16 v[20:23], v[180:183], v[204:207], v[20:23]
	v_mfma_f32_16x16x32_bf16 v[12:15], v[172:175], v[226:229], v[12:15]
	v_mfma_f32_16x16x32_bf16 v[4:7], v[180:183], v[226:229], v[4:7]
	s_barrier
	s_add_i32 s46, s46, 2
	s_add_u32 s18, s18, 0x100
	s_addc_u32 s19, s19, 0
	s_add_u32 s44, s44, 0x100
	s_addc_u32 s45, s45, 0
	s_cmp_gt_u32 s46, 29
	s_cbranch_scc0 .LBB0_1432
	s_branch .Lgemm_after_4

; #define PG8_STAGE(bufoff, gbase, voff) do { _Pragma("unroll") for (int _i = 0; _i < 2; ++_i) \
;         __builtin_amdgcn_global_load_lds((const unsigned*)((const char*)(gbase) + (voff)[_i]), (PG8_LAS unsigned*)(lds + (bufoff) + ldsw + _i * 8192), 16, 0, 0); } while (0)
; #define PG8_LDA(dst, b, h) do { _Pragma("unroll") for (int m = 0; m < 4; ++m) _Pragma("unroll") for (int k = 0; k < 2; ++k) dst[m][k] = *(const PG8_LAS bf16x8*)(lds + PG8_SA(b, h) + aoffk[k] + m * 2048); } while (0)
; #define PG8_WAIT_V(n) asm volatile("s_waitcnt vmcnt(" #n ")" ::: "memory")
; #define PG8_BAR __builtin_amdgcn_s_barrier()
; template <class Epi, class Sched, bool ALIGN_EPI = false, bool SP2 = false>
; __device__ __forceinline__ void gemm_phase(PG8_LAS unsigned char* lds, const Gemm g, const Sched& S, const Epi& E) {
;     ...
;     f32x4 acc[2][2][4][2];
; #pragma unroll
;     for (int a = 0; a < 2; ++a)
; #pragma unroll
;         for (int b = 0; b < 2; ++b)
; #pragma unroll
;             for (int m = 0; m < 4; ++m)
; #pragma unroll
;                 for (int n = 0; n < 2; ++n) acc[a][b][m][n] = (f32x4){0.f, 0.f, 0.f, 0.f};
;     ...
;         const bool has_next = S.next(ui + 1, nxt);
;         const char* nA = has_next ? (const char*)g.A + (size_t)nxt.pm * tstepA + (size_t)nxt.kt0 * kstep : cA; const char* nB = has_next ? (const char*)g.Bt + (size_t)nxt.pn * tstepB + (size_t)nxt.kt0 * kstep : cB;
;         const int nt = cur.nt;
;         for (int t = 0; t < nt; t += 2) {
;             const bool last = (t == nt - 2);
;             const char* a1 = cA + (size_t)(t + 1) * kstep;
;             const char* a2 = last ? nA : cA + (size_t)(t + 2) * kstep; const char* b2 = last ? nB : cB + (size_t)(t + 2) * kstep;
;             const char* a3 = a2 + kstep; const char* b3 = b2 + kstep;
;             if (last && has_next) S.a_ready(nxt);
;             if constexpr (SP2) {
;             PG8_LDB(B0, 0, 0); PG8_LDB(B1, 0, 1); PG8_SCHED; PG8_LDA(At, 0, 0); PG8_STAGE(PG8_SA(1, 1), a1 + hstepA, voffA);
;             PG8_WAIT_V(8); PG8_WAIT_L(0); PG8_BAR; PG8_MMA(0, 0, At, B0); PG8_MMA(0, 1, At, B1); PG8_BAR; PG8_SCHED;
;             PG8_LDA(At, 0, 1); PG8_STAGE(PG8_SB(0, 0), b2, voffB); PG8_STAGE(PG8_SB(0, 1), b2 + hstepB, voffB); PG8_STAGE(PG8_SA(0, 0), a2, voffA);
;             PG8_WAIT_V(8); PG8_WAIT_L(0); PG8_BAR; PG8_MMA(1, 0, At, B0); PG8_MMA(1, 1, At, B1); PG8_BAR; PG8_SCHED;
.LBB0_1591:
	s_add_i32 s7, s43, -2
	s_add_u32 s48, s14, 0x100
	s_addc_u32 s49, s15, 0
	s_mov_b32 s16, 0
	v_readlane_b32 s53, v253, 28
	v_readlane_b32 s54, v253, 29
	v_readlane_b32 s55, v253, 30
	v_readlane_b32 s56, v253, 31
	s_mov_b64 s[58:59], 0x80
.Lgemm_first_5:
	s_add_i32 s50, s16, 2
	s_add_u32 s14, s12, 0x100
	s_addc_u32 s15, s13, 0
	s_add_i32 s51, 0, 0x10000
	s_cmp_eq_u32 s7, s16
	v_add_u32_e32 v142, s51, v145
	s_cselect_b32 s19, s9, s15
	s_cselect_b32 s18, s8, s14
	v_add_u32_e32 v143, s51, v146
	ds_read_b128 v[150:153], v142
	ds_read_b128 v[154:157], v143
	v_add_u32_e32 v142, s53, v145
	s_cselect_b32 s17, s11, s49
	s_cselect_b32 s16, s10, s48
	s_add_i32 s52, 0, 0x14000
	v_add_u32_e32 v143, s53, v146
	ds_read_b128 v[158:161], v142
	ds_read_b128 v[162:165], v143
	v_add_u32_e32 v142, s52, v145
	v_add_u32_e32 v143, s52, v146
	ds_read_b128 v[172:175], v142
	ds_read_b128 v[176:179], v143
	v_add_u32_e32 v142, s54, v145
	v_add_u32_e32 v143, s54, v146
	ds_read_b128 v[180:183], v142
	ds_read_b128 v[184:187], v143
	v_lshl_add_u64 v[142:143], s[12:13], 0, v[138:139]
	s_add_i32 m0, s26, 0xc000
	ds_read_b128 v[188:191], v148
	ds_read_b128 v[192:195], v148 offset:1024
	ds_read_b128 v[196:199], v148 offset:2048
	ds_read_b128 v[200:203], v148 offset:3072
	ds_read_b128 v[204:207], v148 offset:4096
	ds_read_b128 v[208:211], v148 offset:5120
	ds_read_b128 v[226:229], v148 offset:6144
	ds_read_b128 v[230:233], v148 offset:7168
	global_load_lds_dwordx4 v[142:143], off
	v_lshl_add_u64 v[142:143], s[12:13], 0, v[140:141]
	s_add_i32 m0, s26, 0xe000
	s_nop 0
	global_load_lds_dwordx4 v[142:143], off
	s_waitcnt vmcnt(8)
	s_waitcnt lgkmcnt(0)
	s_barrier
	v_mfma_f32_16x16x32_bf16 v[128:131], v[150:153], v[188:191], 0
	v_mfma_f32_16x16x32_bf16 v[124:127], v[158:161], v[188:191], 0
	v_mfma_f32_16x16x32_bf16 v[120:123], v[150:153], v[196:199], 0
	v_mfma_f32_16x16x32_bf16 v[112:115], v[158:161], v[196:199], 0
	v_mfma_f32_16x16x32_bf16 v[104:107], v[150:153], v[204:207], 0
	v_mfma_f32_16x16x32_bf16 v[96:99], v[158:161], v[204:207], 0
	v_mfma_f32_16x16x32_bf16 v[88:91], v[150:153], v[226:229], 0
	v_mfma_f32_16x16x32_bf16 v[80:83], v[158:161], v[226:229], 0
	v_mfma_f32_16x16x32_bf16 v[128:131], v[154:157], v[192:195], v[128:131]
	v_mfma_f32_16x16x32_bf16 v[124:127], v[162:165], v[192:195], v[124:127]
	v_mfma_f32_16x16x32_bf16 v[120:123], v[154:157], v[200:203], v[120:123]
	v_mfma_f32_16x16x32_bf16 v[112:115], v[162:165], v[200:203], v[112:115]
	v_mfma_f32_16x16x32_bf16 v[104:107], v[154:157], v[208:211], v[104:107]
	v_mfma_f32_16x16x32_bf16 v[96:99], v[162:165], v[208:211], v[96:99]
	v_mfma_f32_16x16x32_bf16 v[88:91], v[154:157], v[230:233], v[88:91]
	v_mfma_f32_16x16x32_bf16 v[80:83], v[162:165], v[230:233], v[80:83]
	v_mfma_f32_16x16x32_bf16 v[116:119], v[172:175], v[188:191], 0
	v_mfma_f32_16x16x32_bf16 v[108:111], v[180:183], v[188:191], 0
	v_mfma_f32_16x16x32_bf16 v[100:103], v[172:175], v[196:199], 0
	v_mfma_f32_16x16x32_bf16 v[92:95], v[180:183], v[196:199], 0
	v_mfma_f32_16x16x32_bf16 v[84:87], v[172:175], v[204:207], 0
	v_mfma_f32_16x16x32_bf16 v[76:79], v[180:183], v[204:207], 0
	v_mfma_f32_16x16x32_bf16 v[72:75], v[172:175], v[226:229], 0
	v_mfma_f32_16x16x32_bf16 v[68:71], v[180:183], v[226:229], 0
	v_mfma_f32_16x16x32_bf16 v[116:119], v[176:179], v[192:195], v[116:119]
	v_mfma_f32_16x16x32_bf16 v[108:111], v[184:187], v[192:195], v[108:111]
	v_mfma_f32_16x16x32_bf16 v[100:103], v[176:179], v[200:203], v[100:103]
	v_mfma_f32_16x16x32_bf16 v[92:95], v[184:187], v[200:203], v[92:95]
	v_mfma_f32_16x16x32_bf16 v[84:87], v[176:179], v[208:211], v[84:87]
	v_mfma_f32_16x16x32_bf16 v[76:79], v[184:187], v[208:211], v[76:79]
	v_mfma_f32_16x16x32_bf16 v[72:75], v[176:179], v[230:233], v[72:75]
	v_mfma_f32_16x16x32_bf16 v[68:71], v[184:187], v[230:233], v[68:71]
	s_barrier
	s_add_i32 s12, s51, s25
	v_lshl_add_u64 v[142:143], s[16:17], 0, v[2:3]
	s_mov_b32 m0, s12
	ds_read_b128 v[188:191], v148 offset:16384
	ds_read_b128 v[192:195], v148 offset:17408
	ds_read_b128 v[196:199], v148 offset:18432
	ds_read_b128 v[200:203], v148 offset:19456
	ds_read_b128 v[204:207], v148 offset:20480
	ds_read_b128 v[208:211], v148 offset:21504
	ds_read_b128 v[226:229], v148 offset:22528
	ds_read_b128 v[230:233], v148 offset:23552
	global_load_lds_dwordx4 v[142:143], off
	s_add_i32 m0, s12, 0x2000
	s_add_u32 s12, s16, 0x160000
	v_lshl_add_u64 v[166:167], s[16:17], 0, v[136:137]
	s_addc_u32 s13, s17, 0
	s_add_i32 s51, s52, s25
	global_load_lds_dwordx4 v[166:167], off
	v_lshl_add_u64 v[212:213], s[12:13], 0, v[2:3]
	s_mov_b32 m0, s51
	v_lshl_add_u64 v[220:221], s[18:19], 0, v[134:135]
	global_load_lds_dwordx4 v[212:213], off
	v_lshl_add_u64 v[212:213], s[12:13], 0, v[136:137]
	s_add_i32 m0, s51, 0x2000
	s_nop 0
	global_load_lds_dwordx4 v[212:213], off
	v_lshl_add_u64 v[212:213], s[18:19], 0, v[132:133]
	s_mov_b32 m0, s26
	s_nop 0
	global_load_lds_dwordx4 v[212:213], off
	s_mov_b32 m0, s27
	s_nop 0
	global_load_lds_dwordx4 v[220:221], off
	s_waitcnt vmcnt(8)
	s_waitcnt lgkmcnt(0)
	s_barrier
; #define PG8_STAGE(bufoff, gbase, voff) do { _Pragma("unroll") for (int _i = 0; _i < 2; ++_i) \
;         __builtin_amdgcn_global_load_lds((const unsigned*)((const char*)(gbase) + (voff)[_i]), (PG8_LAS unsigned*)(lds + (bufoff) + ldsw + _i * 8192), 16, 0, 0); } while (0)
; #define PG8_LDA(dst, b, h) do { _Pragma("unroll") for (int m = 0; m < 4; ++m) _Pragma("unroll") for (int k = 0; k < 2; ++k) dst[m][k] = *(const PG8_LAS bf16x8*)(lds + PG8_SA(b, h) + aoffk[k] + m * 2048); } while (0)
; #define PG8_LDB(dst, b, h) do { _Pragma("unroll") for (int n = 0; n < 2; ++n) _Pragma("unroll") for (int k = 0; k < 2; ++k) dst[n][k] = *(const PG8_LAS bf16x8*)(lds + PG8_SB(b, h) + boffk[k] + n * 2048); } while (0)
; #define PG8_MMA(ai, bj, At, Bt) do { __builtin_amdgcn_s_setprio(1); _Pragma("unroll") for (int m = 0; m < 4; ++m) _Pragma("unroll") for (int n = 0; n < 2; ++n) _Pragma("unroll") for (int k = 0; k < 2; ++k) \
;         acc[ai][bj][m][n] = __builtin_amdgcn_mfma_f32_16x16x32_bf16(Bt[n][k], At[m][k], acc[ai][bj][m][n], 0, 0, 0); __builtin_amdgcn_s_setprio(0); } while (0)
; #define PG8_WAIT_V(n) asm volatile("s_waitcnt vmcnt(" #n ")" ::: "memory")
; #define PG8_WAIT_L(n) asm volatile("s_waitcnt lgkmcnt(" #n ")" ::: "memory")
; #define PG8_BAR __builtin_amdgcn_s_barrier()
; #define PG8_SCHED __builtin_amdgcn_sched_barrier(0)
; template <class Epi, class Sched, bool ALIGN_EPI = false, bool SP2 = false>
; __device__ __forceinline__ void gemm_phase(PG8_LAS unsigned char* lds, const Gemm g, const Sched& S, const Epi& E) {
;     ...
;             PG8_LDA(At, 0, 1); PG8_STAGE(PG8_SB(0, 0), b2, voffB); PG8_STAGE(PG8_SB(0, 1), b2 + hstepB, voffB); PG8_STAGE(PG8_SA(0, 0), a2, voffA);
;             PG8_WAIT_V(8); PG8_WAIT_L(0); PG8_BAR; PG8_MMA(1, 0, At, B0); PG8_MMA(1, 1, At, B1); PG8_BAR; PG8_SCHED;
;             PG8_LDB(B0, 1, 0); PG8_LDB(B1, 1, 1); PG8_SCHED; PG8_LDA(At, 1, 0); PG8_STAGE(PG8_SA(0, 1), a2 + hstepA, voffA);
;             PG8_WAIT_V(8); PG8_WAIT_L(0); PG8_BAR; PG8_MMA(0, 0, At, B0); PG8_MMA(0, 1, At, B1); PG8_BAR; PG8_SCHED;
	v_mfma_f32_16x16x32_bf16 v[64:67], v[150:153], v[188:191], 0
	v_mfma_f32_16x16x32_bf16 v[60:63], v[158:161], v[188:191], 0
	v_mfma_f32_16x16x32_bf16 v[56:59], v[150:153], v[196:199], 0
	v_mfma_f32_16x16x32_bf16 v[48:51], v[158:161], v[196:199], 0
	v_mfma_f32_16x16x32_bf16 v[40:43], v[150:153], v[204:207], 0
	v_mfma_f32_16x16x32_bf16 v[32:35], v[158:161], v[204:207], 0
	v_mfma_f32_16x16x32_bf16 v[24:27], v[150:153], v[226:229], 0
	v_mfma_f32_16x16x32_bf16 v[16:19], v[158:161], v[226:229], 0
	v_mfma_f32_16x16x32_bf16 v[64:67], v[154:157], v[192:195], v[64:67]
	v_mfma_f32_16x16x32_bf16 v[60:63], v[162:165], v[192:195], v[60:63]
	v_mfma_f32_16x16x32_bf16 v[56:59], v[154:157], v[200:203], v[56:59]
	v_mfma_f32_16x16x32_bf16 v[48:51], v[162:165], v[200:203], v[48:51]
	v_mfma_f32_16x16x32_bf16 v[40:43], v[154:157], v[208:211], v[40:43]
	v_mfma_f32_16x16x32_bf16 v[32:35], v[162:165], v[208:211], v[32:35]
	v_mfma_f32_16x16x32_bf16 v[24:27], v[154:157], v[230:233], v[24:27]
	v_mfma_f32_16x16x32_bf16 v[16:19], v[162:165], v[230:233], v[16:19]
	v_mfma_f32_16x16x32_bf16 v[52:55], v[172:175], v[188:191], 0
	v_mfma_f32_16x16x32_bf16 v[44:47], v[180:183], v[188:191], 0
	v_mfma_f32_16x16x32_bf16 v[36:39], v[172:175], v[196:199], 0
	v_mfma_f32_16x16x32_bf16 v[28:31], v[180:183], v[196:199], 0
	v_mfma_f32_16x16x32_bf16 v[20:23], v[172:175], v[204:207], 0
	v_mfma_f32_16x16x32_bf16 v[12:15], v[180:183], v[204:207], 0
	v_mfma_f32_16x16x32_bf16 v[8:11], v[172:175], v[226:229], 0
	v_mfma_f32_16x16x32_bf16 v[4:7], v[180:183], v[226:229], 0
	v_mfma_f32_16x16x32_bf16 v[52:55], v[176:179], v[192:195], v[52:55]
	v_mfma_f32_16x16x32_bf16 v[44:47], v[184:187], v[192:195], v[44:47]
	v_mfma_f32_16x16x32_bf16 v[36:39], v[176:179], v[200:203], v[36:39]
	v_mfma_f32_16x16x32_bf16 v[28:31], v[184:187], v[200:203], v[28:31]
	v_mfma_f32_16x16x32_bf16 v[20:23], v[176:179], v[208:211], v[20:23]
	v_mfma_f32_16x16x32_bf16 v[12:15], v[184:187], v[208:211], v[12:15]
	v_mfma_f32_16x16x32_bf16 v[8:11], v[176:179], v[230:233], v[8:11]
	v_mfma_f32_16x16x32_bf16 v[4:7], v[184:187], v[230:233], v[4:7]
	s_barrier
	s_add_i32 s51, 0, 0x18000
	v_add_u32_e32 v149, s51, v145
	v_add_u32_e32 v154, s51, v146
	ds_read_b128 v[150:153], v149
	ds_read_b128 v[154:157], v154
	v_add_u32_e32 v149, s55, v145
	v_add_u32_e32 v162, s55, v146
	s_add_i32 s52, 0, 0x1c000
	ds_read_b128 v[158:161], v149
	ds_read_b128 v[162:165], v162
	v_add_u32_e32 v149, s52, v145
	v_add_u32_e32 v168, s52, v146
	ds_read_b128 v[172:175], v149
	ds_read_b128 v[176:179], v168
	v_add_u32_e32 v149, s56, v145
	v_add_u32_e32 v168, s56, v146
	ds_read_b128 v[180:183], v149
	ds_read_b128 v[184:187], v168
	s_add_u32 s12, s18, 0x160000
	s_addc_u32 s13, s19, 0
	s_mov_b32 m0, s28
	v_lshl_add_u64 v[234:235], s[12:13], 0, v[132:133]
	ds_read_b128 v[188:191], v148 offset:32768
	ds_read_b128 v[192:195], v148 offset:33792
	ds_read_b128 v[196:199], v148 offset:34816
	ds_read_b128 v[200:203], v148 offset:35840
	ds_read_b128 v[204:207], v148 offset:36864
	ds_read_b128 v[208:211], v148 offset:37888
	ds_read_b128 v[226:229], v148 offset:38912
	ds_read_b128 v[230:233], v148 offset:39936
	global_load_lds_dwordx4 v[234:235], off
	v_lshl_add_u64 v[234:235], s[12:13], 0, v[134:135]
	s_mov_b32 m0, s29
	s_nop 0
	global_load_lds_dwordx4 v[234:235], off
	s_waitcnt vmcnt(8)
	s_waitcnt lgkmcnt(0)
	s_barrier
	v_mfma_f32_16x16x32_bf16 v[128:131], v[150:153], v[188:191], v[128:131]
	v_mfma_f32_16x16x32_bf16 v[124:127], v[158:161], v[188:191], v[124:127]
	v_mfma_f32_16x16x32_bf16 v[120:123], v[150:153], v[196:199], v[120:123]
	v_mfma_f32_16x16x32_bf16 v[112:115], v[158:161], v[196:199], v[112:115]
	v_mfma_f32_16x16x32_bf16 v[104:107], v[150:153], v[204:207], v[104:107]
	v_mfma_f32_16x16x32_bf16 v[96:99], v[158:161], v[204:207], v[96:99]
	v_mfma_f32_16x16x32_bf16 v[88:91], v[150:153], v[226:229], v[88:91]
	v_mfma_f32_16x16x32_bf16 v[80:83], v[158:161], v[226:229], v[80:83]
	v_mfma_f32_16x16x32_bf16 v[128:131], v[154:157], v[192:195], v[128:131]
	v_mfma_f32_16x16x32_bf16 v[124:127], v[162:165], v[192:195], v[124:127]
	v_mfma_f32_16x16x32_bf16 v[120:123], v[154:157], v[200:203], v[120:123]
	v_mfma_f32_16x16x32_bf16 v[112:115], v[162:165], v[200:203], v[112:115]
	v_mfma_f32_16x16x32_bf16 v[104:107], v[154:157], v[208:211], v[104:107]
	v_mfma_f32_16x16x32_bf16 v[96:99], v[162:165], v[208:211], v[96:99]
	v_mfma_f32_16x16x32_bf16 v[88:91], v[154:157], v[230:233], v[88:91]
	v_mfma_f32_16x16x32_bf16 v[80:83], v[162:165], v[230:233], v[80:83]
	v_mfma_f32_16x16x32_bf16 v[116:119], v[172:175], v[188:191], v[116:119]
	v_mfma_f32_16x16x32_bf16 v[108:111], v[180:183], v[188:191], v[108:111]
	v_mfma_f32_16x16x32_bf16 v[100:103], v[172:175], v[196:199], v[100:103]
	v_mfma_f32_16x16x32_bf16 v[92:95], v[180:183], v[196:199], v[92:95]
	v_mfma_f32_16x16x32_bf16 v[84:87], v[172:175], v[204:207], v[84:87]
	v_mfma_f32_16x16x32_bf16 v[76:79], v[180:183], v[204:207], v[76:79]
	v_mfma_f32_16x16x32_bf16 v[72:75], v[172:175], v[226:229], v[72:75]
	v_mfma_f32_16x16x32_bf16 v[68:71], v[180:183], v[226:229], v[68:71]
	v_mfma_f32_16x16x32_bf16 v[116:119], v[176:179], v[192:195], v[116:119]
	v_mfma_f32_16x16x32_bf16 v[108:111], v[184:187], v[192:195], v[108:111]
	v_mfma_f32_16x16x32_bf16 v[100:103], v[176:179], v[200:203], v[100:103]
	v_mfma_f32_16x16x32_bf16 v[92:95], v[184:187], v[200:203], v[92:95]
	v_mfma_f32_16x16x32_bf16 v[84:87], v[176:179], v[208:211], v[84:87]
	v_mfma_f32_16x16x32_bf16 v[76:79], v[184:187], v[208:211], v[76:79]
	v_mfma_f32_16x16x32_bf16 v[72:75], v[176:179], v[230:233], v[72:75]
	v_mfma_f32_16x16x32_bf16 v[68:71], v[184:187], v[230:233], v[68:71]
	s_barrier
; #define PG8_STAGE(bufoff, gbase, voff) do { _Pragma("unroll") for (int _i = 0; _i < 2; ++_i) \
;         __builtin_amdgcn_global_load_lds((const unsigned*)((const char*)(gbase) + (voff)[_i]), (PG8_LAS unsigned*)(lds + (bufoff) + ldsw + _i * 8192), 16, 0, 0); } while (0)
; #define PG8_LDA(dst, b, h) do { _Pragma("unroll") for (int m = 0; m < 4; ++m) _Pragma("unroll") for (int k = 0; k < 2; ++k) dst[m][k] = *(const PG8_LAS bf16x8*)(lds + PG8_SA(b, h) + aoffk[k] + m * 2048); } while (0)
; #define PG8_MMA(ai, bj, At, Bt) do { __builtin_amdgcn_s_setprio(1); _Pragma("unroll") for (int m = 0; m < 4; ++m) _Pragma("unroll") for (int n = 0; n < 2; ++n) _Pragma("unroll") for (int k = 0; k < 2; ++k) \
;         acc[ai][bj][m][n] = __builtin_amdgcn_mfma_f32_16x16x32_bf16(Bt[n][k], At[m][k], acc[ai][bj][m][n], 0, 0, 0); __builtin_amdgcn_s_setprio(0); } while (0)
; #define PG8_WAIT_V(n) asm volatile("s_waitcnt vmcnt(" #n ")" ::: "memory")
; #define PG8_WAIT_L(n) asm volatile("s_waitcnt lgkmcnt(" #n ")" ::: "memory")
; #define PG8_BAR __builtin_amdgcn_s_barrier()
; #define PG8_SCHED __builtin_amdgcn_sched_barrier(0)
; template <class Epi, class Sched, bool ALIGN_EPI = false, bool SP2 = false>
; __device__ __forceinline__ void gemm_phase(PG8_LAS unsigned char* lds, const Gemm g, const Sched& S, const Epi& E) {
;     ...
;         for (int t = 0; t < nt; t += 2) {
;             const bool last = (t == nt - 2);
;             const char* a1 = cA + (size_t)(t + 1) * kstep;
;             const char* a2 = last ? nA : cA + (size_t)(t + 2) * kstep; const char* b2 = last ? nB : cB + (size_t)(t + 2) * kstep;
;             const char* a3 = a2 + kstep; const char* b3 = b2 + kstep;
;     ...
;             PG8_LDA(At, 1, 1); PG8_STAGE(PG8_SB(1, 0), b3, voffB); PG8_STAGE(PG8_SB(1, 1), b3 + hstepB, voffB); PG8_STAGE(PG8_SA(1, 0), a3, voffA);
;             PG8_WAIT_V(8); PG8_WAIT_L(0); PG8_BAR; PG8_MMA(1, 0, At, B0); PG8_MMA(1, 1, At, B1); PG8_BAR; PG8_SCHED;
	s_add_i32 s12, s51, s25
	v_lshl_add_u64 v[142:143], v[142:143], 0, s[58:59]
	s_mov_b32 m0, s12
	ds_read_b128 v[188:191], v148 offset:49152
	ds_read_b128 v[192:195], v148 offset:50176
	ds_read_b128 v[196:199], v148 offset:51200
	ds_read_b128 v[200:203], v148 offset:52224
	ds_read_b128 v[204:207], v148 offset:53248
	ds_read_b128 v[208:211], v148 offset:54272
	ds_read_b128 v[226:229], v148 offset:55296
	ds_read_b128 v[230:233], v148 offset:56320
	global_load_lds_dwordx4 v[142:143], off
	s_add_i32 m0, s12, 0x2000
	s_add_u32 s12, s16, 0x160080
	v_lshl_add_u64 v[142:143], v[166:167], 0, s[58:59]
	s_addc_u32 s13, s17, 0
	s_add_i32 s16, s52, s25
	global_load_lds_dwordx4 v[142:143], off
	v_lshl_add_u64 v[142:143], s[12:13], 0, v[2:3]
	s_mov_b32 m0, s16
	s_nop 0
	global_load_lds_dwordx4 v[142:143], off
	v_lshl_add_u64 v[142:143], s[12:13], 0, v[136:137]
	s_add_i32 m0, s16, 0x2000
	s_nop 0
	global_load_lds_dwordx4 v[142:143], off
	v_lshl_add_u64 v[142:143], v[212:213], 0, s[58:59]
	s_mov_b32 m0, s36
	s_nop 0
	global_load_lds_dwordx4 v[142:143], off
	v_lshl_add_u64 v[142:143], v[220:221], 0, s[58:59]
	s_mov_b32 m0, s37
	s_nop 0
	global_load_lds_dwordx4 v[142:143], off
	s_waitcnt vmcnt(8)
	s_waitcnt lgkmcnt(0)
	s_barrier
	v_mfma_f32_16x16x32_bf16 v[64:67], v[150:153], v[188:191], v[64:67]
	v_mfma_f32_16x16x32_bf16 v[60:63], v[158:161], v[188:191], v[60:63]
	v_mfma_f32_16x16x32_bf16 v[56:59], v[150:153], v[196:199], v[56:59]
	v_mfma_f32_16x16x32_bf16 v[48:51], v[158:161], v[196:199], v[48:51]
	v_mfma_f32_16x16x32_bf16 v[40:43], v[150:153], v[204:207], v[40:43]
	v_mfma_f32_16x16x32_bf16 v[32:35], v[158:161], v[204:207], v[32:35]
	v_mfma_f32_16x16x32_bf16 v[24:27], v[150:153], v[226:229], v[24:27]
	v_mfma_f32_16x16x32_bf16 v[16:19], v[158:161], v[226:229], v[16:19]
	v_mfma_f32_16x16x32_bf16 v[64:67], v[154:157], v[192:195], v[64:67]
	v_mfma_f32_16x16x32_bf16 v[60:63], v[162:165], v[192:195], v[60:63]
	v_mfma_f32_16x16x32_bf16 v[56:59], v[154:157], v[200:203], v[56:59]
	v_mfma_f32_16x16x32_bf16 v[48:51], v[162:165], v[200:203], v[48:51]
	v_mfma_f32_16x16x32_bf16 v[40:43], v[154:157], v[208:211], v[40:43]
	v_mfma_f32_16x16x32_bf16 v[32:35], v[162:165], v[208:211], v[32:35]
	v_mfma_f32_16x16x32_bf16 v[24:27], v[154:157], v[230:233], v[24:27]
	v_mfma_f32_16x16x32_bf16 v[16:19], v[162:165], v[230:233], v[16:19]
	v_mfma_f32_16x16x32_bf16 v[52:55], v[172:175], v[188:191], v[52:55]
	v_mfma_f32_16x16x32_bf16 v[44:47], v[180:183], v[188:191], v[44:47]
	v_mfma_f32_16x16x32_bf16 v[36:39], v[172:175], v[196:199], v[36:39]
	v_mfma_f32_16x16x32_bf16 v[28:31], v[180:183], v[196:199], v[28:31]
	v_mfma_f32_16x16x32_bf16 v[20:23], v[172:175], v[204:207], v[20:23]
	v_mfma_f32_16x16x32_bf16 v[12:15], v[180:183], v[204:207], v[12:15]
	v_mfma_f32_16x16x32_bf16 v[8:11], v[172:175], v[226:229], v[8:11]
	v_mfma_f32_16x16x32_bf16 v[4:7], v[180:183], v[226:229], v[4:7]
	v_mfma_f32_16x16x32_bf16 v[52:55], v[176:179], v[192:195], v[52:55]
	v_mfma_f32_16x16x32_bf16 v[44:47], v[184:187], v[192:195], v[44:47]
	v_mfma_f32_16x16x32_bf16 v[36:39], v[176:179], v[200:203], v[36:39]
	v_mfma_f32_16x16x32_bf16 v[28:31], v[184:187], v[200:203], v[28:31]
	v_mfma_f32_16x16x32_bf16 v[20:23], v[176:179], v[208:211], v[20:23]
	v_mfma_f32_16x16x32_bf16 v[12:15], v[184:187], v[208:211], v[12:15]
	v_mfma_f32_16x16x32_bf16 v[8:11], v[176:179], v[230:233], v[8:11]
	v_mfma_f32_16x16x32_bf16 v[4:7], v[184:187], v[230:233], v[4:7]
	s_barrier
	s_add_u32 s48, s48, 0x100
	s_addc_u32 s49, s49, 0
	s_cmp_ge_i32 s50, s43
	s_mov_b64 s[12:13], s[14:15]
	s_mov_b32 s16, s50
	s_cbranch_scc0 .LBB0_1592
	s_branch .Lgemm_after_5
